# decode stream rewritten by hand (transpose-reduce scores, DPP scan, rolling loads) with workgroup-level dequeue of 8 heads per key block, all four instances
# speedup vs baseline: 1.0198x; 1.0198x over previous
; __device__ __forceinline__ void sb_decode_stream(Frame& F, unsigned* qctr, int base, int limit) {
;     const float* CK = kin(2); const float* CV = kin(3); const int* PT = (const int*)kin(4);
;     int lane = F.lane; asm volatile("" : "+v"(lane));
;     const int half = lane >> 5, l32 = lane & 31;
;     const float k1 = SB_SCALE * 1.4426950408889634f;
;     const size_t lo = (size_t)half * (NH * HD) + 4 * l32;
;     int it;
;     { const unsigned v = __hip_atomic_fetch_add(qctr, 1u, __ATOMIC_RELAXED, __HIP_MEMORY_SCOPE_AGENT);
;       it = (int)(__builtin_amdgcn_readfirstlane(v) >> 6); if (it >= limit) return; it += base; }
;     f32x4 A[16], B[16], q4;
;     size_t cb;
;     { const int b = it >> 11, h = it & 7, p0 = ((it >> 3) & 255) * 64;
;       const int page = PT[b * NPAGES + (p0 >> 7)];
;       cb = (((size_t)page * PAGE + (p0 & 127)) * NH + h) * HD + lo;
;       q4 = *(const f32x4*)(SSP(S_PROJ) + (size_t)b * IN_COLS + h * HD + 4 * l32);
; #pragma unroll
;       for (int i = 0; i < 16; ++i) A[i] = __builtin_nontemporal_load((const f32x4*)(CK + cb + (size_t)(2 * i) * (NH * HD)));
; #pragma unroll
;       for (int i = 0; i < 16; ++i) B[i] = __builtin_nontemporal_load((const f32x4*)(CK + cb + (size_t)(32 + 2 * i) * (NH * HD))); }
; __global__ void __launch_bounds__(NWAVES * 64, 2) hymba_fwd(Args args) {
;     ...
;     if (IN(2)) { _Pragma("unroll") for (int rep = 0; rep < NREP(2); ++rep) {
;         const bool streamer = (F.bid % 3) == 0 && F.bid < 252;
;         if (streamer) sb_decode_stream(F, F.ctl + CW_QUEUE, 0, DEC_Q2);
.LBB0_1119:
	s_cmp_lt_i32 s84, 3
	s_cselect_b64 s[2:3], -1, 0
	s_cmp_gt_i32 s85, 2
	s_cselect_b64 s[4:5], -1, 0
	s_and_b64 s[2:3], s[2:3], s[4:5]
	s_andn2_b64 vcc, exec, s[2:3]
	s_cbranch_vccnz .LBB0_1376
	s_mul_i32 s2, s96, 0xaaaaaaab
	s_add_i32 s2, s2, 0x2aaaaaaa
	s_cmp_lt_u32 s2, 0x55555555
	s_cselect_b64 s[2:3], -1, 0
	s_cmpk_lt_i32 s96, 0xfc
	s_cselect_b64 s[4:5], -1, 0
	s_and_b64 s[42:43], s[4:5], s[2:3]
	s_add_u32 s40, s26, 0x1000
	s_addc_u32 s41, s27, 0
	s_add_u32 s38, s26, 0x2ff18000
	s_addc_u32 s39, s27, 0
	s_add_u32 s3, s26, 0x2ff70400
	s_addc_u32 s4, s27, 0
	s_and_b64 vcc, exec, s[42:43]
	s_cbranch_vccz .LBB0_1132
	s_load_dwordx2 s[50:51], s[0:1], 0x10
	s_load_dwordx2 s[52:53], s[0:1], 0x18
	s_load_dwordx2 s[54:55], s[0:1], 0x20
	s_load_dwordx2 s[56:57], s[0:1], 0x60
	s_add_u32 s58, s26, 0x1000
	s_addc_u32 s59, s27, 0
	s_add_u32 s60, s26, 0x2ff18000
	s_addc_u32 s61, s27, 0
	s_add_u32 s62, s26, 0x2ff70400
	s_addc_u32 s63, s27, 0
	s_mov_b32 s76, 0xcccccccc
	s_mov_b32 s77, 0xcccccccc
	s_mov_b32 s78, 0xaaaaaaaa
	s_mov_b32 s79, 0xaaaaaaaa
	v_and_b32_e32 v193, 31, v199
	v_lshrrev_b32_e32 v188, 5, v199
	v_lshlrev_b32_e32 v193, 4, v193
	v_lshl_add_u32 v187, v188, 12, v193
	v_lshlrev_b32_e32 v188, 7, v188
	v_mov_b32_e32 v189, 0
	v_mov_b32_e32 v190, 64
	v_mov_b32_e32 v190, 0x200
	s_mov_b32 s37, 0x251e0
	s_cmp_eq_u32 s94, 0
	s_cbranch_scc0 .Ldqa_pro
	s_mov_b64 exec, 1
	global_atomic_add v191, v189, v190, s[58:59] sc0
	s_mov_b64 exec, -1
.Ldqa_pro:
	s_waitcnt vmcnt(0)
	v_readfirstlane_b32 s2, v191
	v_mov_b32_e32 v200, s37
	s_cmp_eq_u32 s94, 0
	s_cbranch_scc0 .Ldqa_sh1
	v_mov_b32_e32 v201, s2
	ds_write_b32 v200, v201
	s_waitcnt lgkmcnt(0)
.Ldqa_sh1:
	s_barrier
	ds_read_b32 v201, v200
	s_xor_b32 s37, s37, 4
	s_waitcnt lgkmcnt(0)
	v_readfirstlane_b32 s2, v201
	s_nop 0
	s_lshr_b32 s72, s2, 6
	s_cmp_ge_u32 s72, 0x1800
	s_cbranch_scc1 .Ldqa_exit
	s_add_u32 s72, s72, s94
	s_min_u32 s72, s72, 0x17ff
	s_mov_b32 s74, s72
	s_mov_b32 s75, 0
	s_waitcnt lgkmcnt(0)
	s_lshr_b32 s6, s72, 11
	s_and_b32 s7, s72, 7
	s_bfe_u32 s8, s72, 0x80003
	s_lshl_b32 s9, s6, 7
	s_lshr_b32 s10, s8, 1
	s_or_b32 s9, s9, s10
	s_lshl_b32 s9, s9, 2
	s_lshl_b32 s10, s7, 2
	s_load_dword s29, s[54:55], s9
	s_load_dword s30, s[56:57], s10
	s_waitcnt lgkmcnt(0)
	s_mov_b32 s12, s29
	s_mov_b32 s13, 0
	s_lshl_b64 s[12:13], s[12:13], 19
	s_and_b32 s14, s8, 1
	s_lshl_b32 s14, s14, 18
	s_lshl_b32 s15, s7, 9
	s_or_b32 s14, s14, s15
	s_or_b32 s80, s12, s14
	s_mov_b32 s81, s13
	s_add_u32 s64, s50, s80
	s_addc_u32 s65, s51, s81
	s_mul_i32 s16, s6, 0x7040
	s_add_u32 s16, s16, s15
	s_add_u32 s16, s60, s16
	s_addc_u32 s17, s61, 0
	global_load_dwordx4 v[156:159], v193, s[16:17]
	global_load_dwordx4 v[4:7], v187, s[64:65] nt
	s_add_u32 s64, s64, 0x2000
	s_addc_u32 s65, s65, 0
	global_load_dwordx4 v[8:11], v187, s[64:65] nt
	s_add_u32 s64, s64, 0x2000
	s_addc_u32 s65, s65, 0
	global_load_dwordx4 v[12:15], v187, s[64:65] nt
	s_add_u32 s64, s64, 0x2000
	s_addc_u32 s65, s65, 0
	global_load_dwordx4 v[16:19], v187, s[64:65] nt
	s_add_u32 s64, s64, 0x2000
	s_addc_u32 s65, s65, 0
	global_load_dwordx4 v[20:23], v187, s[64:65] nt
	s_add_u32 s64, s64, 0x2000
	s_addc_u32 s65, s65, 0
	global_load_dwordx4 v[24:27], v187, s[64:65] nt
	s_add_u32 s64, s64, 0x2000
	s_addc_u32 s65, s65, 0
	global_load_dwordx4 v[28:31], v187, s[64:65] nt
	s_add_u32 s64, s64, 0x2000
	s_addc_u32 s65, s65, 0
	global_load_dwordx4 v[32:35], v187, s[64:65] nt
	s_add_u32 s64, s64, 0x2000
	s_addc_u32 s65, s65, 0
	global_load_dwordx4 v[36:39], v187, s[64:65] nt
	s_add_u32 s64, s64, 0x2000
	s_addc_u32 s65, s65, 0
	global_load_dwordx4 v[40:43], v187, s[64:65] nt
	s_add_u32 s64, s64, 0x2000
	s_addc_u32 s65, s65, 0
	global_load_dwordx4 v[44:47], v187, s[64:65] nt
	s_add_u32 s64, s64, 0x2000
	s_addc_u32 s65, s65, 0
	global_load_dwordx4 v[48:51], v187, s[64:65] nt
	s_add_u32 s64, s64, 0x2000
	s_addc_u32 s65, s65, 0
	global_load_dwordx4 v[52:55], v187, s[64:65] nt
	s_add_u32 s64, s64, 0x2000
	s_addc_u32 s65, s65, 0
	global_load_dwordx4 v[56:59], v187, s[64:65] nt
	s_add_u32 s64, s64, 0x2000
	s_addc_u32 s65, s65, 0
	global_load_dwordx4 v[60:63], v187, s[64:65] nt
	s_add_u32 s64, s64, 0x2000
	s_addc_u32 s65, s65, 0
	global_load_dwordx4 v[64:67], v187, s[64:65] nt
	s_add_u32 s64, s64, 0x2000
	s_addc_u32 s65, s65, 0
	global_load_dwordx4 v[68:71], v187, s[64:65] nt
	s_add_u32 s64, s64, 0x2000
	s_addc_u32 s65, s65, 0
	global_load_dwordx4 v[72:75], v187, s[64:65] nt
	s_add_u32 s64, s64, 0x2000
	s_addc_u32 s65, s65, 0
	global_load_dwordx4 v[76:79], v187, s[64:65] nt
	s_add_u32 s64, s64, 0x2000
	s_addc_u32 s65, s65, 0
	global_load_dwordx4 v[80:83], v187, s[64:65] nt
	s_add_u32 s64, s64, 0x2000
	s_addc_u32 s65, s65, 0
	global_load_dwordx4 v[84:87], v187, s[64:65] nt
	s_add_u32 s64, s64, 0x2000
	s_addc_u32 s65, s65, 0
	global_load_dwordx4 v[88:91], v187, s[64:65] nt
	s_add_u32 s64, s64, 0x2000
	s_addc_u32 s65, s65, 0
	global_load_dwordx4 v[92:95], v187, s[64:65] nt
	s_add_u32 s64, s64, 0x2000
	s_addc_u32 s65, s65, 0
	global_load_dwordx4 v[96:99], v187, s[64:65] nt
	s_add_u32 s64, s64, 0x2000
	s_addc_u32 s65, s65, 0
	global_load_dwordx4 v[100:103], v187, s[64:65] nt
	s_add_u32 s64, s64, 0x2000
	s_addc_u32 s65, s65, 0
	global_load_dwordx4 v[104:107], v187, s[64:65] nt
	s_add_u32 s64, s64, 0x2000
	s_addc_u32 s65, s65, 0
	global_load_dwordx4 v[108:111], v187, s[64:65] nt
	s_add_u32 s64, s64, 0x2000
	s_addc_u32 s65, s65, 0
	global_load_dwordx4 v[112:115], v187, s[64:65] nt
	s_add_u32 s64, s64, 0x2000
	s_addc_u32 s65, s65, 0
	global_load_dwordx4 v[116:119], v187, s[64:65] nt
	s_add_u32 s64, s64, 0x2000
	s_addc_u32 s65, s65, 0
	global_load_dwordx4 v[120:123], v187, s[64:65] nt
	s_add_u32 s64, s64, 0x2000
	s_addc_u32 s65, s65, 0
	global_load_dwordx4 v[124:127], v187, s[64:65] nt
	s_add_u32 s64, s64, 0x2000
	s_addc_u32 s65, s65, 0
	global_load_dwordx4 v[128:131], v187, s[64:65] nt
	s_add_u32 s64, s64, 0x2000
	s_addc_u32 s65, s65, 0
	global_load_dword v194, v189, s[58:59]
	global_load_dword v195, v189, s[58:59]
; __device__ __forceinline__ void sb_decode_stream(Frame& F, unsigned* qctr, int base, int limit) {
;     ...
;     for (;;) {
;         const int bh = ((it >> 11) << 3) | (it & 7), blk = (it >> 3) & 255, h = it & 7;
;         const unsigned vn = __hip_atomic_fetch_add(qctr, 1u, __ATOMIC_RELAXED, __HIP_MEMORY_SCOPE_AGENT);
;         const float k2 = kin(12)[h] * 1.4426950408889634f;
;         int zi = 0;
;     ...
;         DEC_SCORES(A, 0);
; #pragma unroll
;         for (int i = 0; i < 16; ++i) A[i] = __builtin_nontemporal_load((const f32x4*)(CV + cb + (size_t)(2 * i) * (NH * HD)));
;         DEC_SCORES(B, 1);
;     ...
; #pragma unroll
;         for (int i = 0; i < 16; ++i) B[i] = __builtin_nontemporal_load((const f32x4*)(CV + cb + (size_t)(32 + 2 * i) * (NH * HD)));
.Ldqa_loop:
	s_nop 0
	s_mov_b32 s28, s30
	s_mov_b32 s68, s80
	s_mov_b32 s69, s81
	s_cmp_eq_u32 s94, 0
	s_cbranch_scc0 .Ldqa_fetch
	s_mov_b64 exec, 1
	global_atomic_add v191, v189, v190, s[58:59] sc0
	s_mov_b64 exec, -1
	s_branch .Ldqa_fetched
.Ldqa_fetch:
	s_nop 4
	global_load_dword v194, v189, s[54:55]
.Ldqa_fetched:
	s_nop 0
	s_add_u32 s66, s52, s68
	s_addc_u32 s67, s53, s69
	s_lshr_b32 s18, s72, 11
	s_lshl_b32 s18, s18, 3
	s_and_b32 s19, s72, 7
	s_or_b32 s18, s18, s19
	s_lshl_b32 s18, s18, 8
	s_bfe_u32 s19, s72, 0x80003
	s_or_b32 s18, s18, s19
	s_mul_i32 s18, s18, 0x210
	s_add_u32 s70, s62, s18
	s_addc_u32 s71, s63, 0
	v_mov_b32_e32 v192, s28
	v_mul_f32_e32 v192, 0x3fb8aa3b, v192
	s_waitcnt vmcnt(34)
	v_mov_b32_e32 v152, v156
	v_mov_b32_e32 v153, v157
	v_mov_b32_e32 v154, v158
	v_mov_b32_e32 v155, v159
	v_pk_mul_f32 v[148:149], v[4:5], v[152:153]
	v_pk_fma_f32 v[148:149], v[6:7], v[154:155], v[148:149]
	global_load_dwordx4 v[4:7], v187, s[66:67] nt
	s_add_u32 s66, s66, 0x2000
	s_addc_u32 s67, s67, 0
	v_add_f32_e32 v132, v148, v149
	s_waitcnt vmcnt(34)
	v_pk_mul_f32 v[150:151], v[8:9], v[152:153]
	v_pk_fma_f32 v[150:151], v[10:11], v[154:155], v[150:151]
	global_load_dwordx4 v[8:11], v187, s[66:67] nt
	s_add_u32 s66, s66, 0x2000
	s_addc_u32 s67, s67, 0
	v_add_f32_e32 v133, v150, v151
	s_waitcnt vmcnt(34)
	v_pk_mul_f32 v[148:149], v[12:13], v[152:153]
	v_pk_fma_f32 v[148:149], v[14:15], v[154:155], v[148:149]
	global_load_dwordx4 v[12:15], v187, s[66:67] nt
	s_add_u32 s66, s66, 0x2000
	s_addc_u32 s67, s67, 0
	v_add_f32_e32 v134, v148, v149
	s_waitcnt vmcnt(34)
	v_pk_mul_f32 v[150:151], v[16:17], v[152:153]
	v_pk_fma_f32 v[150:151], v[18:19], v[154:155], v[150:151]
	global_load_dwordx4 v[16:19], v187, s[66:67] nt
	s_add_u32 s66, s66, 0x2000
	s_addc_u32 s67, s67, 0
	v_add_f32_e32 v135, v150, v151
	s_waitcnt vmcnt(34)
	v_pk_mul_f32 v[148:149], v[20:21], v[152:153]
	v_pk_fma_f32 v[148:149], v[22:23], v[154:155], v[148:149]
	global_load_dwordx4 v[20:23], v187, s[66:67] nt
	s_add_u32 s66, s66, 0x2000
	s_addc_u32 s67, s67, 0
	v_add_f32_e32 v136, v148, v149
	s_waitcnt vmcnt(34)
	v_pk_mul_f32 v[150:151], v[24:25], v[152:153]
	v_pk_fma_f32 v[150:151], v[26:27], v[154:155], v[150:151]
	global_load_dwordx4 v[24:27], v187, s[66:67] nt
	s_add_u32 s66, s66, 0x2000
	s_addc_u32 s67, s67, 0
	v_add_f32_e32 v137, v150, v151
	s_waitcnt vmcnt(34)
	v_pk_mul_f32 v[148:149], v[28:29], v[152:153]
	v_pk_fma_f32 v[148:149], v[30:31], v[154:155], v[148:149]
	global_load_dwordx4 v[28:31], v187, s[66:67] nt
	s_add_u32 s66, s66, 0x2000
	s_addc_u32 s67, s67, 0
	v_add_f32_e32 v138, v148, v149
	s_waitcnt vmcnt(34)
	v_pk_mul_f32 v[150:151], v[32:33], v[152:153]
	v_pk_fma_f32 v[150:151], v[34:35], v[154:155], v[150:151]
	global_load_dwordx4 v[32:35], v187, s[66:67] nt
	s_add_u32 s66, s66, 0x2000
	s_addc_u32 s67, s67, 0
	v_add_f32_e32 v139, v150, v151
	s_waitcnt vmcnt(34)
	v_pk_mul_f32 v[148:149], v[36:37], v[152:153]
	v_pk_fma_f32 v[148:149], v[38:39], v[154:155], v[148:149]
	global_load_dwordx4 v[36:39], v187, s[66:67] nt
	s_add_u32 s66, s66, 0x2000
	s_addc_u32 s67, s67, 0
	v_add_f32_e32 v140, v148, v149
	s_waitcnt vmcnt(34)
	v_pk_mul_f32 v[150:151], v[40:41], v[152:153]
	v_pk_fma_f32 v[150:151], v[42:43], v[154:155], v[150:151]
	global_load_dwordx4 v[40:43], v187, s[66:67] nt
	s_add_u32 s66, s66, 0x2000
	s_addc_u32 s67, s67, 0
	v_add_f32_e32 v141, v150, v151
	s_waitcnt vmcnt(34)
	v_pk_mul_f32 v[148:149], v[44:45], v[152:153]
	v_pk_fma_f32 v[148:149], v[46:47], v[154:155], v[148:149]
	global_load_dwordx4 v[44:47], v187, s[66:67] nt
	s_add_u32 s66, s66, 0x2000
	s_addc_u32 s67, s67, 0
	v_add_f32_e32 v142, v148, v149
	s_waitcnt vmcnt(34)
	v_pk_mul_f32 v[150:151], v[48:49], v[152:153]
	v_pk_fma_f32 v[150:151], v[50:51], v[154:155], v[150:151]
	global_load_dwordx4 v[48:51], v187, s[66:67] nt
	s_add_u32 s66, s66, 0x2000
	s_addc_u32 s67, s67, 0
	v_add_f32_e32 v143, v150, v151
	s_waitcnt vmcnt(34)
	v_pk_mul_f32 v[148:149], v[52:53], v[152:153]
	v_pk_fma_f32 v[148:149], v[54:55], v[154:155], v[148:149]
	global_load_dwordx4 v[52:55], v187, s[66:67] nt
	s_add_u32 s66, s66, 0x2000
	s_addc_u32 s67, s67, 0
	v_add_f32_e32 v144, v148, v149
	s_waitcnt vmcnt(34)
	v_pk_mul_f32 v[150:151], v[56:57], v[152:153]
	v_pk_fma_f32 v[150:151], v[58:59], v[154:155], v[150:151]
	global_load_dwordx4 v[56:59], v187, s[66:67] nt
	s_add_u32 s66, s66, 0x2000
	s_addc_u32 s67, s67, 0
	v_add_f32_e32 v145, v150, v151
	s_waitcnt vmcnt(34)
	v_pk_mul_f32 v[148:149], v[60:61], v[152:153]
	v_pk_fma_f32 v[148:149], v[62:63], v[154:155], v[148:149]
	global_load_dwordx4 v[60:63], v187, s[66:67] nt
	s_add_u32 s66, s66, 0x2000
	s_addc_u32 s67, s67, 0
	v_add_f32_e32 v146, v148, v149
	s_waitcnt vmcnt(34)
; __device__ __forceinline__ void sb_decode_stream(Frame& F, unsigned* qctr, int base, int limit) {
;     ...
;         DEC_SCORES(A, 0);
; #pragma unroll
;         for (int i = 0; i < 16; ++i) A[i] = __builtin_nontemporal_load((const f32x4*)(CV + cb + (size_t)(2 * i) * (NH * HD)));
;         DEC_SCORES(B, 1);
	v_pk_mul_f32 v[150:151], v[64:65], v[152:153]
	v_pk_fma_f32 v[150:151], v[66:67], v[154:155], v[150:151]
	global_load_dwordx4 v[64:67], v187, s[66:67] nt
	s_add_u32 s66, s66, 0x2000
	s_addc_u32 s67, s67, 0
	v_add_f32_e32 v147, v150, v151
	v_add_f32_dpp v132, v132, v132 row_ror:8 row_mask:0xf bank_mask:0x3
	v_add_f32_dpp v133, v133, v133 row_ror:8 row_mask:0xf bank_mask:0x3
	v_add_f32_dpp v134, v134, v134 row_ror:8 row_mask:0xf bank_mask:0x3
	v_add_f32_dpp v135, v135, v135 row_ror:8 row_mask:0xf bank_mask:0x3
	v_add_f32_dpp v136, v136, v136 row_ror:8 row_mask:0xf bank_mask:0x3
	v_add_f32_dpp v137, v137, v137 row_ror:8 row_mask:0xf bank_mask:0x3
	v_add_f32_dpp v138, v138, v138 row_ror:8 row_mask:0xf bank_mask:0x3
	v_add_f32_dpp v139, v139, v139 row_ror:8 row_mask:0xf bank_mask:0x3
	v_add_f32_dpp v132, v140, v140 row_ror:8 row_mask:0xf bank_mask:0xc
	v_add_f32_dpp v133, v141, v141 row_ror:8 row_mask:0xf bank_mask:0xc
	v_add_f32_dpp v134, v142, v142 row_ror:8 row_mask:0xf bank_mask:0xc
	v_add_f32_dpp v135, v143, v143 row_ror:8 row_mask:0xf bank_mask:0xc
	v_add_f32_dpp v136, v144, v144 row_ror:8 row_mask:0xf bank_mask:0xc
	v_add_f32_dpp v137, v145, v145 row_ror:8 row_mask:0xf bank_mask:0xc
	v_add_f32_dpp v138, v146, v146 row_ror:8 row_mask:0xf bank_mask:0xc
	v_add_f32_dpp v139, v147, v147 row_ror:8 row_mask:0xf bank_mask:0xc
	v_add_f32_dpp v132, v132, v132 row_ror:12 row_mask:0xf bank_mask:0x5
	v_add_f32_dpp v133, v133, v133 row_ror:12 row_mask:0xf bank_mask:0x5
	v_add_f32_dpp v134, v134, v134 row_ror:12 row_mask:0xf bank_mask:0x5
	v_add_f32_dpp v135, v135, v135 row_ror:12 row_mask:0xf bank_mask:0x5
	v_add_f32_dpp v132, v136, v136 row_ror:4 row_mask:0xf bank_mask:0xa
	v_add_f32_dpp v133, v137, v137 row_ror:4 row_mask:0xf bank_mask:0xa
	v_add_f32_dpp v134, v138, v138 row_ror:4 row_mask:0xf bank_mask:0xa
	v_add_f32_dpp v135, v139, v139 row_ror:4 row_mask:0xf bank_mask:0xa
	v_add_f32_dpp v140, v132, v132 quad_perm:[2,3,0,1] row_mask:0xf bank_mask:0xf
	v_add_f32_dpp v142, v134, v134 quad_perm:[2,3,0,1] row_mask:0xf bank_mask:0xf
	v_add_f32_dpp v141, v133, v133 quad_perm:[2,3,0,1] row_mask:0xf bank_mask:0xf
	v_add_f32_dpp v143, v135, v135 quad_perm:[2,3,0,1] row_mask:0xf bank_mask:0xf
	v_cndmask_b32_e64 v132, v140, v142, s[76:77]
	v_cndmask_b32_e64 v133, v141, v143, s[76:77]
	s_nop 0
	v_add_f32_dpp v196, v132, v132 quad_perm:[1,0,3,2] row_mask:0xf bank_mask:0xf
	v_add_f32_dpp v197, v133, v133 quad_perm:[1,0,3,2] row_mask:0xf bank_mask:0xf
	v_cndmask_b32_e64 v176, v196, v197, s[78:79]
	s_waitcnt vmcnt(34)
	v_pk_mul_f32 v[148:149], v[68:69], v[152:153]
	v_pk_fma_f32 v[148:149], v[70:71], v[154:155], v[148:149]
	global_load_dwordx4 v[68:71], v187, s[66:67] nt
	s_add_u32 s66, s66, 0x2000
	s_addc_u32 s67, s67, 0
	v_add_f32_e32 v132, v148, v149
	s_waitcnt vmcnt(34)
	v_pk_mul_f32 v[150:151], v[72:73], v[152:153]
	v_pk_fma_f32 v[150:151], v[74:75], v[154:155], v[150:151]
	global_load_dwordx4 v[72:75], v187, s[66:67] nt
	s_add_u32 s66, s66, 0x2000
	s_addc_u32 s67, s67, 0
	v_add_f32_e32 v133, v150, v151
	s_waitcnt vmcnt(34)
	v_pk_mul_f32 v[148:149], v[76:77], v[152:153]
	v_pk_fma_f32 v[148:149], v[78:79], v[154:155], v[148:149]
	global_load_dwordx4 v[76:79], v187, s[66:67] nt
	s_add_u32 s66, s66, 0x2000
	s_addc_u32 s67, s67, 0
	v_add_f32_e32 v134, v148, v149
	s_waitcnt vmcnt(34)
	v_pk_mul_f32 v[150:151], v[80:81], v[152:153]
	v_pk_fma_f32 v[150:151], v[82:83], v[154:155], v[150:151]
	global_load_dwordx4 v[80:83], v187, s[66:67] nt
	s_add_u32 s66, s66, 0x2000
	s_addc_u32 s67, s67, 0
	v_add_f32_e32 v135, v150, v151
	s_waitcnt vmcnt(34)
	v_pk_mul_f32 v[148:149], v[84:85], v[152:153]
	v_pk_fma_f32 v[148:149], v[86:87], v[154:155], v[148:149]
	global_load_dwordx4 v[84:87], v187, s[66:67] nt
	s_add_u32 s66, s66, 0x2000
	s_addc_u32 s67, s67, 0
	v_add_f32_e32 v136, v148, v149
	s_waitcnt vmcnt(34)
	v_pk_mul_f32 v[150:151], v[88:89], v[152:153]
	v_pk_fma_f32 v[150:151], v[90:91], v[154:155], v[150:151]
	global_load_dwordx4 v[88:91], v187, s[66:67] nt
	s_add_u32 s66, s66, 0x2000
	s_addc_u32 s67, s67, 0
	v_add_f32_e32 v137, v150, v151
	s_waitcnt vmcnt(34)
	v_pk_mul_f32 v[148:149], v[92:93], v[152:153]
	v_pk_fma_f32 v[148:149], v[94:95], v[154:155], v[148:149]
	global_load_dwordx4 v[92:95], v187, s[66:67] nt
	s_add_u32 s66, s66, 0x2000
	s_addc_u32 s67, s67, 0
	v_add_f32_e32 v138, v148, v149
	s_waitcnt vmcnt(34)
	v_pk_mul_f32 v[150:151], v[96:97], v[152:153]
	v_pk_fma_f32 v[150:151], v[98:99], v[154:155], v[150:151]
	global_load_dwordx4 v[96:99], v187, s[66:67] nt
	s_add_u32 s66, s66, 0x2000
	s_addc_u32 s67, s67, 0
	v_add_f32_e32 v139, v150, v151
	s_waitcnt vmcnt(34)
	v_pk_mul_f32 v[148:149], v[100:101], v[152:153]
	v_pk_fma_f32 v[148:149], v[102:103], v[154:155], v[148:149]
	global_load_dwordx4 v[100:103], v187, s[66:67] nt
	s_add_u32 s66, s66, 0x2000
	s_addc_u32 s67, s67, 0
	v_add_f32_e32 v140, v148, v149
	s_waitcnt vmcnt(34)
	v_pk_mul_f32 v[150:151], v[104:105], v[152:153]
	v_pk_fma_f32 v[150:151], v[106:107], v[154:155], v[150:151]
	global_load_dwordx4 v[104:107], v187, s[66:67] nt
	s_add_u32 s66, s66, 0x2000
	s_addc_u32 s67, s67, 0
	v_add_f32_e32 v141, v150, v151
	s_waitcnt vmcnt(34)
	v_pk_mul_f32 v[148:149], v[108:109], v[152:153]
	v_pk_fma_f32 v[148:149], v[110:111], v[154:155], v[148:149]
	global_load_dwordx4 v[108:111], v187, s[66:67] nt
	s_add_u32 s66, s66, 0x2000
	s_addc_u32 s67, s67, 0
	v_add_f32_e32 v142, v148, v149
	s_waitcnt vmcnt(34)
	v_pk_mul_f32 v[150:151], v[112:113], v[152:153]
	v_pk_fma_f32 v[150:151], v[114:115], v[154:155], v[150:151]
	global_load_dwordx4 v[112:115], v187, s[66:67] nt
	s_add_u32 s66, s66, 0x2000
	s_addc_u32 s67, s67, 0
	v_add_f32_e32 v143, v150, v151
	s_waitcnt vmcnt(34)
	v_pk_mul_f32 v[148:149], v[116:117], v[152:153]
	v_pk_fma_f32 v[148:149], v[118:119], v[154:155], v[148:149]
	global_load_dwordx4 v[116:119], v187, s[66:67] nt
	s_add_u32 s66, s66, 0x2000
	s_addc_u32 s67, s67, 0
	v_add_f32_e32 v144, v148, v149
	s_waitcnt vmcnt(34)
	v_pk_mul_f32 v[150:151], v[120:121], v[152:153]
	v_pk_fma_f32 v[150:151], v[122:123], v[154:155], v[150:151]
	global_load_dwordx4 v[120:123], v187, s[66:67] nt
	s_add_u32 s66, s66, 0x2000
	s_addc_u32 s67, s67, 0
	v_add_f32_e32 v145, v150, v151
	s_waitcnt vmcnt(34)
	v_pk_mul_f32 v[148:149], v[124:125], v[152:153]
	v_pk_fma_f32 v[148:149], v[126:127], v[154:155], v[148:149]
	global_load_dwordx4 v[124:127], v187, s[66:67] nt
	s_add_u32 s66, s66, 0x2000
	s_addc_u32 s67, s67, 0
	v_add_f32_e32 v146, v148, v149
	s_waitcnt vmcnt(34)
	v_pk_mul_f32 v[150:151], v[128:129], v[152:153]
	v_pk_fma_f32 v[150:151], v[130:131], v[154:155], v[150:151]
	global_load_dwordx4 v[128:131], v187, s[66:67] nt
	s_add_u32 s66, s66, 0x2000
	s_addc_u32 s67, s67, 0
	v_add_f32_e32 v147, v150, v151
	s_waitcnt vmcnt(32)
	v_readfirstlane_b32 s2, v191
	v_mov_b32_e32 v200, s37
	s_cmp_eq_u32 s94, 0
	s_cbranch_scc0 .Ldqa_sh2
	v_mov_b32_e32 v201, s2
	ds_write_b32 v200, v201
	s_waitcnt lgkmcnt(0)
; __device__ __forceinline__ void sb_decode_stream(Frame& F, unsigned* qctr, int base, int limit) {
;     ...
;         const int bh = ((it >> 11) << 3) | (it & 7), blk = (it >> 3) & 255, h = it & 7;
;         const unsigned vn = __hip_atomic_fetch_add(qctr, 1u, __ATOMIC_RELAXED, __HIP_MEMORY_SCOPE_AGENT);
;         const float k2 = kin(12)[h] * 1.4426950408889634f;
;         int zi = 0;
;     ...
;         DEC_SCORES(A, 0);
; #pragma unroll
;         for (int i = 0; i < 16; ++i) A[i] = __builtin_nontemporal_load((const f32x4*)(CV + cb + (size_t)(2 * i) * (NH * HD)));
;         DEC_SCORES(B, 1);
;     ...
; #pragma unroll
;         for (int i = 0; i < 16; ++i) B[i] = __builtin_nontemporal_load((const f32x4*)(CV + cb + (size_t)(32 + 2 * i) * (NH * HD)));
;         const float z = __builtin_bit_cast(float, zi);
;         const float e = __builtin_amdgcn_exp2f(-(z * k1 + k2));
;         const float be = __builtin_amdgcn_rcpf(1.0f + e), m = 1.0f - be;
;         float s = m;
; #pragma unroll
;         for (int o = 1; o < 64; o <<= 1) { const float t = __shfl_down(s, o); if (lane + o < 64) s *= t; }
;         const float tot = __shfl(s, 0);
;         const float sx = __shfl_down(s, 1);
;         const float a = be * (lane < 63 ? sx : 1.0f);
;         int itn = (int)(__builtin_amdgcn_readfirstlane(vn) >> 6); const bool more = itn < limit; itn = more ? itn + base : it;
;         const int bn = itn >> 11, hn = itn & 7, p0n = ((itn >> 3) & 255) * 64;
;         const int pagen = PT[bn * NPAGES + (p0n >> 7)];
;         const size_t cbn = (((size_t)pagen * PAGE + (p0n & 127)) * NH + hn) * HD + lo;
;         const size_t stepn = more ? (size_t)(NH * HD) : 0;
.Ldqa_sh2:
	s_barrier
	ds_read_b32 v201, v200
	s_xor_b32 s37, s37, 4
	s_waitcnt lgkmcnt(0)
	v_readfirstlane_b32 s2, v201
	s_nop 0
	s_lshr_b32 s73, s2, 6
	s_cmp_lt_u32 s73, 0x1800
	s_cselect_b32 s31, 1, 0
	s_add_u32 s73, s73, s94
	s_min_u32 s73, s73, 0x17ff
	s_cmp_eq_u32 s31, 1
	s_cselect_b32 s73, s73, s72
	s_lshr_b32 s6, s73, 11
	s_and_b32 s7, s73, 7
	s_bfe_u32 s8, s73, 0x80003
	s_lshl_b32 s9, s6, 7
	s_lshr_b32 s10, s8, 1
	s_or_b32 s9, s9, s10
	s_lshl_b32 s9, s9, 2
	s_lshl_b32 s10, s7, 2
	s_load_dword s29, s[54:55], s9
	s_load_dword s30, s[56:57], s10
	v_add_f32_dpp v132, v132, v132 row_ror:8 row_mask:0xf bank_mask:0x3
	v_add_f32_dpp v133, v133, v133 row_ror:8 row_mask:0xf bank_mask:0x3
	v_add_f32_dpp v134, v134, v134 row_ror:8 row_mask:0xf bank_mask:0x3
	v_add_f32_dpp v135, v135, v135 row_ror:8 row_mask:0xf bank_mask:0x3
	v_add_f32_dpp v136, v136, v136 row_ror:8 row_mask:0xf bank_mask:0x3
	v_add_f32_dpp v137, v137, v137 row_ror:8 row_mask:0xf bank_mask:0x3
	v_add_f32_dpp v138, v138, v138 row_ror:8 row_mask:0xf bank_mask:0x3
	v_add_f32_dpp v139, v139, v139 row_ror:8 row_mask:0xf bank_mask:0x3
	v_add_f32_dpp v132, v140, v140 row_ror:8 row_mask:0xf bank_mask:0xc
	v_add_f32_dpp v133, v141, v141 row_ror:8 row_mask:0xf bank_mask:0xc
	v_add_f32_dpp v134, v142, v142 row_ror:8 row_mask:0xf bank_mask:0xc
	v_add_f32_dpp v135, v143, v143 row_ror:8 row_mask:0xf bank_mask:0xc
	v_add_f32_dpp v136, v144, v144 row_ror:8 row_mask:0xf bank_mask:0xc
	v_add_f32_dpp v137, v145, v145 row_ror:8 row_mask:0xf bank_mask:0xc
	v_add_f32_dpp v138, v146, v146 row_ror:8 row_mask:0xf bank_mask:0xc
	v_add_f32_dpp v139, v147, v147 row_ror:8 row_mask:0xf bank_mask:0xc
	v_add_f32_dpp v132, v132, v132 row_ror:12 row_mask:0xf bank_mask:0x5
	v_add_f32_dpp v133, v133, v133 row_ror:12 row_mask:0xf bank_mask:0x5
	v_add_f32_dpp v134, v134, v134 row_ror:12 row_mask:0xf bank_mask:0x5
	v_add_f32_dpp v135, v135, v135 row_ror:12 row_mask:0xf bank_mask:0x5
	v_add_f32_dpp v132, v136, v136 row_ror:4 row_mask:0xf bank_mask:0xa
	v_add_f32_dpp v133, v137, v137 row_ror:4 row_mask:0xf bank_mask:0xa
	v_add_f32_dpp v134, v138, v138 row_ror:4 row_mask:0xf bank_mask:0xa
	v_add_f32_dpp v135, v139, v139 row_ror:4 row_mask:0xf bank_mask:0xa
	v_add_f32_dpp v140, v132, v132 quad_perm:[2,3,0,1] row_mask:0xf bank_mask:0xf
	v_add_f32_dpp v142, v134, v134 quad_perm:[2,3,0,1] row_mask:0xf bank_mask:0xf
	v_add_f32_dpp v141, v133, v133 quad_perm:[2,3,0,1] row_mask:0xf bank_mask:0xf
	v_add_f32_dpp v143, v135, v135 quad_perm:[2,3,0,1] row_mask:0xf bank_mask:0xf
	v_cndmask_b32_e64 v132, v140, v142, s[76:77]
	v_cndmask_b32_e64 v133, v141, v143, s[76:77]
	s_nop 0
	v_add_f32_dpp v196, v132, v132 quad_perm:[1,0,3,2] row_mask:0xf bank_mask:0xf
	v_add_f32_dpp v197, v133, v133 quad_perm:[1,0,3,2] row_mask:0xf bank_mask:0xf
	v_cndmask_b32_e64 v177, v196, v197, s[78:79]
	s_nop 1
	v_permlane16_swap_b32_e32 v176, v177
	v_add_f32_e32 v178, v176, v177
	v_mul_f32_e32 v178, 0x3e0293ee, v178
	v_add_f32_e32 v178, v178, v192
	v_exp_f32_e64 v198, -v178
	s_nop 0
	v_add_f32_e32 v198, 1.0, v198
	v_rcp_f32_e32 v179, v198
	s_nop 0
	v_sub_f32_e32 v180, 1.0, v179
	v_mov_b32_e32 v181, v180
	s_nop 1
	v_permlane32_swap_b32_e32 v180, v181
	v_mul_f32_e32 v183, v180, v181
	s_nop 1
	v_mul_f32_dpp v183, v183, v183 row_shl:1 row_mask:0xf bank_mask:0xf
	s_nop 1
	v_mul_f32_dpp v183, v183, v183 row_shl:2 row_mask:0xf bank_mask:0xf
	s_nop 1
	v_mul_f32_dpp v183, v183, v183 row_shl:4 row_mask:0xf bank_mask:0xf
	s_nop 1
	v_mul_f32_dpp v183, v183, v183 row_shl:8 row_mask:0xf bank_mask:0xf
	s_nop 0
	v_readlane_b32 s33, v183, 16
	v_mov_b32_e32 v184, 1.0
	s_nop 0
	v_mov_b32_e32 v185, s33
	s_nop 1
	v_mul_f32_dpp v183, v183, v185 quad_perm:[0,1,2,3] row_mask:0x5 bank_mask:0xf
	v_mov_b32_dpp v184, v185 quad_perm:[0,1,2,3] row_mask:0x5 bank_mask:0xf
	s_nop 1
	v_mov_b32_dpp v184, v183 row_shl:1 row_mask:0xf bank_mask:0xf
	v_mul_f32_e32 v186, v179, v184
	s_nop 1
	v_mul_f32_dpp v186, v186, v181 quad_perm:[0,1,2,3] row_mask:0x3 bank_mask:0xf
	s_cmp_eq_u32 s31, 0
	s_cbranch_scc1 .Ldqa_tail
	s_waitcnt lgkmcnt(0)
	s_mov_b32 s12, s29
	s_mov_b32 s13, 0
	s_lshl_b64 s[12:13], s[12:13], 19
	s_and_b32 s14, s8, 1
	s_lshl_b32 s14, s14, 18
	s_lshl_b32 s15, s7, 9
	s_or_b32 s14, s14, s15
	s_or_b32 s80, s12, s14
	s_mov_b32 s81, s13
	s_add_u32 s64, s50, s80
	s_addc_u32 s65, s51, s81
	s_mul_i32 s16, s6, 0x7040
	s_add_u32 s16, s16, s15
	s_add_u32 s16, s60, s16
	s_addc_u32 s17, s61, 0
	global_load_dwordx4 v[156:159], v193, s[16:17]
	v_mov_b32_e32 v160, 0
	v_mov_b32_e32 v161, 0
	v_mov_b32_e32 v162, 0
	v_mov_b32_e32 v163, 0
	v_mov_b32_e32 v164, 0
	v_mov_b32_e32 v165, 0
	v_mov_b32_e32 v166, 0
	v_mov_b32_e32 v167, 0
	ds_bpermute_b32 v168, v188, v186 offset:0
	ds_bpermute_b32 v170, v188, v186 offset:4
	ds_bpermute_b32 v172, v188, v186 offset:8
	ds_bpermute_b32 v174, v188, v186 offset:12
	s_waitcnt vmcnt(32) lgkmcnt(3)
	v_pk_fma_f32 v[160:161], v[4:5], v[168:169], v[160:161] op_sel_hi:[1,0,1]
	v_pk_fma_f32 v[162:163], v[6:7], v[168:169], v[162:163] op_sel_hi:[1,0,1]
	global_load_dwordx4 v[4:7], v187, s[64:65] nt
	s_add_u32 s64, s64, 0x2000
	s_addc_u32 s65, s65, 0
	ds_bpermute_b32 v168, v188, v186 offset:16
	s_waitcnt vmcnt(32) lgkmcnt(3)
	v_pk_fma_f32 v[164:165], v[8:9], v[170:171], v[164:165] op_sel_hi:[1,0,1]
	v_pk_fma_f32 v[166:167], v[10:11], v[170:171], v[166:167] op_sel_hi:[1,0,1]
	global_load_dwordx4 v[8:11], v187, s[64:65] nt
	s_add_u32 s64, s64, 0x2000
	s_addc_u32 s65, s65, 0
	ds_bpermute_b32 v170, v188, v186 offset:20
	s_waitcnt vmcnt(32) lgkmcnt(3)
; __device__ __forceinline__ void sb_decode_stream(Frame& F, unsigned* qctr, int base, int limit) {
;     ...
;         f32x4 o4 = {0.f, 0.f, 0.f, 0.f};
; #pragma unroll
;         for (int i = 0; i < 16; ++i) { const float aj = __shfl(a, 2 * i + half); o4 += aj * A[i]; }
;         const f32x4 q4n = *(const f32x4*)(SSP(S_PROJ) + (size_t)bn * IN_COLS + hn * HD + 4 * l32);
; #pragma unroll
;         for (int i = 0; i < 16; ++i) A[i] = __builtin_nontemporal_load((const f32x4*)(CK + cbn + (size_t)(2 * i) * stepn));
; #pragma unroll
;         for (int i = 0; i < 16; ++i) { const float aj = __shfl(a, 32 + 2 * i + half); o4 += aj * B[i]; }
	v_pk_fma_f32 v[160:161], v[12:13], v[172:173], v[160:161] op_sel_hi:[1,0,1]
	v_pk_fma_f32 v[162:163], v[14:15], v[172:173], v[162:163] op_sel_hi:[1,0,1]
	global_load_dwordx4 v[12:15], v187, s[64:65] nt
	s_add_u32 s64, s64, 0x2000
	s_addc_u32 s65, s65, 0
	ds_bpermute_b32 v172, v188, v186 offset:24
	s_waitcnt vmcnt(32) lgkmcnt(3)
	v_pk_fma_f32 v[164:165], v[16:17], v[174:175], v[164:165] op_sel_hi:[1,0,1]
	v_pk_fma_f32 v[166:167], v[18:19], v[174:175], v[166:167] op_sel_hi:[1,0,1]
	global_load_dwordx4 v[16:19], v187, s[64:65] nt
	s_add_u32 s64, s64, 0x2000
	s_addc_u32 s65, s65, 0
	ds_bpermute_b32 v174, v188, v186 offset:28
	s_waitcnt vmcnt(32) lgkmcnt(3)
	v_pk_fma_f32 v[160:161], v[20:21], v[168:169], v[160:161] op_sel_hi:[1,0,1]
	v_pk_fma_f32 v[162:163], v[22:23], v[168:169], v[162:163] op_sel_hi:[1,0,1]
	global_load_dwordx4 v[20:23], v187, s[64:65] nt
	s_add_u32 s64, s64, 0x2000
	s_addc_u32 s65, s65, 0
	ds_bpermute_b32 v168, v188, v186 offset:32
	s_waitcnt vmcnt(32) lgkmcnt(3)
	v_pk_fma_f32 v[164:165], v[24:25], v[170:171], v[164:165] op_sel_hi:[1,0,1]
	v_pk_fma_f32 v[166:167], v[26:27], v[170:171], v[166:167] op_sel_hi:[1,0,1]
	global_load_dwordx4 v[24:27], v187, s[64:65] nt
	s_add_u32 s64, s64, 0x2000
	s_addc_u32 s65, s65, 0
	ds_bpermute_b32 v170, v188, v186 offset:36
	s_waitcnt vmcnt(32) lgkmcnt(3)
	v_pk_fma_f32 v[160:161], v[28:29], v[172:173], v[160:161] op_sel_hi:[1,0,1]
	v_pk_fma_f32 v[162:163], v[30:31], v[172:173], v[162:163] op_sel_hi:[1,0,1]
	global_load_dwordx4 v[28:31], v187, s[64:65] nt
	s_add_u32 s64, s64, 0x2000
	s_addc_u32 s65, s65, 0
	ds_bpermute_b32 v172, v188, v186 offset:40
	s_waitcnt vmcnt(32) lgkmcnt(3)
	v_pk_fma_f32 v[164:165], v[32:33], v[174:175], v[164:165] op_sel_hi:[1,0,1]
	v_pk_fma_f32 v[166:167], v[34:35], v[174:175], v[166:167] op_sel_hi:[1,0,1]
	global_load_dwordx4 v[32:35], v187, s[64:65] nt
	s_add_u32 s64, s64, 0x2000
	s_addc_u32 s65, s65, 0
	ds_bpermute_b32 v174, v188, v186 offset:44
	s_waitcnt vmcnt(32) lgkmcnt(3)
	v_pk_fma_f32 v[160:161], v[36:37], v[168:169], v[160:161] op_sel_hi:[1,0,1]
	v_pk_fma_f32 v[162:163], v[38:39], v[168:169], v[162:163] op_sel_hi:[1,0,1]
	global_load_dwordx4 v[36:39], v187, s[64:65] nt
	s_add_u32 s64, s64, 0x2000
	s_addc_u32 s65, s65, 0
	ds_bpermute_b32 v168, v188, v186 offset:48
	s_waitcnt vmcnt(32) lgkmcnt(3)
	v_pk_fma_f32 v[164:165], v[40:41], v[170:171], v[164:165] op_sel_hi:[1,0,1]
	v_pk_fma_f32 v[166:167], v[42:43], v[170:171], v[166:167] op_sel_hi:[1,0,1]
	global_load_dwordx4 v[40:43], v187, s[64:65] nt
	s_add_u32 s64, s64, 0x2000
	s_addc_u32 s65, s65, 0
	ds_bpermute_b32 v170, v188, v186 offset:52
	s_waitcnt vmcnt(32) lgkmcnt(3)
	v_pk_fma_f32 v[160:161], v[44:45], v[172:173], v[160:161] op_sel_hi:[1,0,1]
	v_pk_fma_f32 v[162:163], v[46:47], v[172:173], v[162:163] op_sel_hi:[1,0,1]
	global_load_dwordx4 v[44:47], v187, s[64:65] nt
	s_add_u32 s64, s64, 0x2000
	s_addc_u32 s65, s65, 0
	ds_bpermute_b32 v172, v188, v186 offset:56
	s_waitcnt vmcnt(32) lgkmcnt(3)
	v_pk_fma_f32 v[164:165], v[48:49], v[174:175], v[164:165] op_sel_hi:[1,0,1]
	v_pk_fma_f32 v[166:167], v[50:51], v[174:175], v[166:167] op_sel_hi:[1,0,1]
	global_load_dwordx4 v[48:51], v187, s[64:65] nt
	s_add_u32 s64, s64, 0x2000
	s_addc_u32 s65, s65, 0
	ds_bpermute_b32 v174, v188, v186 offset:60
	s_waitcnt vmcnt(32) lgkmcnt(3)
	v_pk_fma_f32 v[160:161], v[52:53], v[168:169], v[160:161] op_sel_hi:[1,0,1]
	v_pk_fma_f32 v[162:163], v[54:55], v[168:169], v[162:163] op_sel_hi:[1,0,1]
	global_load_dwordx4 v[52:55], v187, s[64:65] nt
	s_add_u32 s64, s64, 0x2000
	s_addc_u32 s65, s65, 0
	ds_bpermute_b32 v168, v188, v186 offset:64
	s_waitcnt vmcnt(32) lgkmcnt(3)
	v_pk_fma_f32 v[164:165], v[56:57], v[170:171], v[164:165] op_sel_hi:[1,0,1]
	v_pk_fma_f32 v[166:167], v[58:59], v[170:171], v[166:167] op_sel_hi:[1,0,1]
	global_load_dwordx4 v[56:59], v187, s[64:65] nt
	s_add_u32 s64, s64, 0x2000
	s_addc_u32 s65, s65, 0
	ds_bpermute_b32 v170, v188, v186 offset:68
	s_waitcnt vmcnt(32) lgkmcnt(3)
	v_pk_fma_f32 v[160:161], v[60:61], v[172:173], v[160:161] op_sel_hi:[1,0,1]
	v_pk_fma_f32 v[162:163], v[62:63], v[172:173], v[162:163] op_sel_hi:[1,0,1]
	global_load_dwordx4 v[60:63], v187, s[64:65] nt
	s_add_u32 s64, s64, 0x2000
	s_addc_u32 s65, s65, 0
	ds_bpermute_b32 v172, v188, v186 offset:72
	s_waitcnt vmcnt(32) lgkmcnt(3)
	v_pk_fma_f32 v[164:165], v[64:65], v[174:175], v[164:165] op_sel_hi:[1,0,1]
	v_pk_fma_f32 v[166:167], v[66:67], v[174:175], v[166:167] op_sel_hi:[1,0,1]
	global_load_dwordx4 v[64:67], v187, s[64:65] nt
	s_add_u32 s64, s64, 0x2000
	s_addc_u32 s65, s65, 0
	ds_bpermute_b32 v174, v188, v186 offset:76
	s_waitcnt vmcnt(32) lgkmcnt(3)
	v_pk_fma_f32 v[160:161], v[68:69], v[168:169], v[160:161] op_sel_hi:[1,0,1]
	v_pk_fma_f32 v[162:163], v[70:71], v[168:169], v[162:163] op_sel_hi:[1,0,1]
	global_load_dwordx4 v[68:71], v187, s[64:65] nt
	s_add_u32 s64, s64, 0x2000
	s_addc_u32 s65, s65, 0
	ds_bpermute_b32 v168, v188, v186 offset:80
	s_waitcnt vmcnt(32) lgkmcnt(3)
	v_pk_fma_f32 v[164:165], v[72:73], v[170:171], v[164:165] op_sel_hi:[1,0,1]
	v_pk_fma_f32 v[166:167], v[74:75], v[170:171], v[166:167] op_sel_hi:[1,0,1]
	global_load_dwordx4 v[72:75], v187, s[64:65] nt
	s_add_u32 s64, s64, 0x2000
	s_addc_u32 s65, s65, 0
	ds_bpermute_b32 v170, v188, v186 offset:84
	s_waitcnt vmcnt(32) lgkmcnt(3)
	v_pk_fma_f32 v[160:161], v[76:77], v[172:173], v[160:161] op_sel_hi:[1,0,1]
	v_pk_fma_f32 v[162:163], v[78:79], v[172:173], v[162:163] op_sel_hi:[1,0,1]
	global_load_dwordx4 v[76:79], v187, s[64:65] nt
	s_add_u32 s64, s64, 0x2000
	s_addc_u32 s65, s65, 0
	ds_bpermute_b32 v172, v188, v186 offset:88
	s_waitcnt vmcnt(32) lgkmcnt(3)
; __device__ __forceinline__ void sb_decode_stream(Frame& F, unsigned* qctr, int base, int limit) {
;     ...
;         for (int i = 0; i < 16; ++i) { const float aj = __shfl(a, 2 * i + half); o4 += aj * A[i]; }
;         const f32x4 q4n = *(const f32x4*)(SSP(S_PROJ) + (size_t)bn * IN_COLS + hn * HD + 4 * l32);
; #pragma unroll
;         for (int i = 0; i < 16; ++i) A[i] = __builtin_nontemporal_load((const f32x4*)(CK + cbn + (size_t)(2 * i) * stepn));
; #pragma unroll
;         for (int i = 0; i < 16; ++i) { const float aj = __shfl(a, 32 + 2 * i + half); o4 += aj * B[i]; }
; #pragma unroll
;         for (int i = 0; i < 16; ++i) B[i] = __builtin_nontemporal_load((const f32x4*)(CK + cbn + (size_t)(32 + 2 * i) * stepn));
;         o4.x += __shfl_xor(o4.x, 32); o4.y += __shfl_xor(o4.y, 32); o4.z += __shfl_xor(o4.z, 32); o4.w += __shfl_xor(o4.w, 32);
;         float* P = SSP(S_PART) + ((size_t)bh * DSEG + blk) * DPART;
;         if (half == 0) *(f32x4*)(P + 4 * l32) = o4; if (lane == 0) P[128] = tot;
;         if (!more) break;
;         it = itn; cb = cbn; q4 = q4n;
	v_pk_fma_f32 v[164:165], v[80:81], v[174:175], v[164:165] op_sel_hi:[1,0,1]
	v_pk_fma_f32 v[166:167], v[82:83], v[174:175], v[166:167] op_sel_hi:[1,0,1]
	global_load_dwordx4 v[80:83], v187, s[64:65] nt
	s_add_u32 s64, s64, 0x2000
	s_addc_u32 s65, s65, 0
	ds_bpermute_b32 v174, v188, v186 offset:92
	s_waitcnt vmcnt(32) lgkmcnt(3)
	v_pk_fma_f32 v[160:161], v[84:85], v[168:169], v[160:161] op_sel_hi:[1,0,1]
	v_pk_fma_f32 v[162:163], v[86:87], v[168:169], v[162:163] op_sel_hi:[1,0,1]
	global_load_dwordx4 v[84:87], v187, s[64:65] nt
	s_add_u32 s64, s64, 0x2000
	s_addc_u32 s65, s65, 0
	ds_bpermute_b32 v168, v188, v186 offset:96
	s_waitcnt vmcnt(32) lgkmcnt(3)
	v_pk_fma_f32 v[164:165], v[88:89], v[170:171], v[164:165] op_sel_hi:[1,0,1]
	v_pk_fma_f32 v[166:167], v[90:91], v[170:171], v[166:167] op_sel_hi:[1,0,1]
	global_load_dwordx4 v[88:91], v187, s[64:65] nt
	s_add_u32 s64, s64, 0x2000
	s_addc_u32 s65, s65, 0
	ds_bpermute_b32 v170, v188, v186 offset:100
	s_waitcnt vmcnt(32) lgkmcnt(3)
	v_pk_fma_f32 v[160:161], v[92:93], v[172:173], v[160:161] op_sel_hi:[1,0,1]
	v_pk_fma_f32 v[162:163], v[94:95], v[172:173], v[162:163] op_sel_hi:[1,0,1]
	global_load_dwordx4 v[92:95], v187, s[64:65] nt
	s_add_u32 s64, s64, 0x2000
	s_addc_u32 s65, s65, 0
	ds_bpermute_b32 v172, v188, v186 offset:104
	s_waitcnt vmcnt(32) lgkmcnt(3)
	v_pk_fma_f32 v[164:165], v[96:97], v[174:175], v[164:165] op_sel_hi:[1,0,1]
	v_pk_fma_f32 v[166:167], v[98:99], v[174:175], v[166:167] op_sel_hi:[1,0,1]
	global_load_dwordx4 v[96:99], v187, s[64:65] nt
	s_add_u32 s64, s64, 0x2000
	s_addc_u32 s65, s65, 0
	ds_bpermute_b32 v174, v188, v186 offset:108
	s_waitcnt vmcnt(32) lgkmcnt(3)
	v_pk_fma_f32 v[160:161], v[100:101], v[168:169], v[160:161] op_sel_hi:[1,0,1]
	v_pk_fma_f32 v[162:163], v[102:103], v[168:169], v[162:163] op_sel_hi:[1,0,1]
	global_load_dwordx4 v[100:103], v187, s[64:65] nt
	s_add_u32 s64, s64, 0x2000
	s_addc_u32 s65, s65, 0
	ds_bpermute_b32 v168, v188, v186 offset:112
	s_waitcnt vmcnt(32) lgkmcnt(3)
	v_pk_fma_f32 v[164:165], v[104:105], v[170:171], v[164:165] op_sel_hi:[1,0,1]
	v_pk_fma_f32 v[166:167], v[106:107], v[170:171], v[166:167] op_sel_hi:[1,0,1]
	global_load_dwordx4 v[104:107], v187, s[64:65] nt
	s_add_u32 s64, s64, 0x2000
	s_addc_u32 s65, s65, 0
	ds_bpermute_b32 v170, v188, v186 offset:116
	s_waitcnt vmcnt(32) lgkmcnt(3)
	v_pk_fma_f32 v[160:161], v[108:109], v[172:173], v[160:161] op_sel_hi:[1,0,1]
	v_pk_fma_f32 v[162:163], v[110:111], v[172:173], v[162:163] op_sel_hi:[1,0,1]
	global_load_dwordx4 v[108:111], v187, s[64:65] nt
	s_add_u32 s64, s64, 0x2000
	s_addc_u32 s65, s65, 0
	ds_bpermute_b32 v172, v188, v186 offset:120
	s_waitcnt vmcnt(32) lgkmcnt(3)
	v_pk_fma_f32 v[164:165], v[112:113], v[174:175], v[164:165] op_sel_hi:[1,0,1]
	v_pk_fma_f32 v[166:167], v[114:115], v[174:175], v[166:167] op_sel_hi:[1,0,1]
	global_load_dwordx4 v[112:115], v187, s[64:65] nt
	s_add_u32 s64, s64, 0x2000
	s_addc_u32 s65, s65, 0
	ds_bpermute_b32 v174, v188, v186 offset:124
	s_waitcnt vmcnt(32) lgkmcnt(3)
	v_pk_fma_f32 v[160:161], v[116:117], v[168:169], v[160:161] op_sel_hi:[1,0,1]
	v_pk_fma_f32 v[162:163], v[118:119], v[168:169], v[162:163] op_sel_hi:[1,0,1]
	global_load_dwordx4 v[116:119], v187, s[64:65] nt
	s_add_u32 s64, s64, 0x2000
	s_addc_u32 s65, s65, 0
	s_waitcnt vmcnt(32) lgkmcnt(2)
	v_pk_fma_f32 v[164:165], v[120:121], v[170:171], v[164:165] op_sel_hi:[1,0,1]
	v_pk_fma_f32 v[166:167], v[122:123], v[170:171], v[166:167] op_sel_hi:[1,0,1]
	global_load_dwordx4 v[120:123], v187, s[64:65] nt
	s_add_u32 s64, s64, 0x2000
	s_addc_u32 s65, s65, 0
	s_waitcnt vmcnt(32) lgkmcnt(1)
	v_pk_fma_f32 v[160:161], v[124:125], v[172:173], v[160:161] op_sel_hi:[1,0,1]
	v_pk_fma_f32 v[162:163], v[126:127], v[172:173], v[162:163] op_sel_hi:[1,0,1]
	global_load_dwordx4 v[124:127], v187, s[64:65] nt
	s_add_u32 s64, s64, 0x2000
	s_addc_u32 s65, s65, 0
	s_waitcnt vmcnt(32) lgkmcnt(0)
	v_pk_fma_f32 v[164:165], v[128:129], v[174:175], v[164:165] op_sel_hi:[1,0,1]
	v_pk_fma_f32 v[166:167], v[130:131], v[174:175], v[166:167] op_sel_hi:[1,0,1]
	global_load_dwordx4 v[128:131], v187, s[64:65] nt
	s_add_u32 s64, s64, 0x2000
	s_addc_u32 s65, s65, 0
	v_pk_add_f32 v[160:161], v[160:161], v[164:165]
	v_pk_add_f32 v[162:163], v[162:163], v[166:167]
	v_mov_b32_e32 v164, v160
	v_mov_b32_e32 v165, v161
	v_mov_b32_e32 v166, v162
	v_mov_b32_e32 v167, v163
	v_permlane32_swap_b32_e32 v160, v164
	v_permlane32_swap_b32_e32 v161, v165
	v_permlane32_swap_b32_e32 v162, v166
	v_permlane32_swap_b32_e32 v163, v167
	v_pk_add_f32 v[160:161], v[160:161], v[164:165]
	v_pk_add_f32 v[162:163], v[162:163], v[166:167]
	s_mov_b32 exec_hi, 0
	global_store_dwordx4 v193, v[160:163], s[70:71]
	s_mov_b32 exec_lo, 1
	global_store_dword v189, v183, s[70:71] offset:512
	s_mov_b64 exec, -1
	s_mov_b32 s72, s73
	s_branch .Ldqa_loop
; __device__ __forceinline__ void sb_decode_stream(Frame& F, unsigned* qctr, int base, int limit) {
;     ...
;         f32x4 o4 = {0.f, 0.f, 0.f, 0.f};
; #pragma unroll
;         for (int i = 0; i < 16; ++i) { const float aj = __shfl(a, 2 * i + half); o4 += aj * A[i]; }
;         const f32x4 q4n = *(const f32x4*)(SSP(S_PROJ) + (size_t)bn * IN_COLS + hn * HD + 4 * l32);
; #pragma unroll
;         for (int i = 0; i < 16; ++i) A[i] = __builtin_nontemporal_load((const f32x4*)(CK + cbn + (size_t)(2 * i) * stepn));
; #pragma unroll
;         for (int i = 0; i < 16; ++i) { const float aj = __shfl(a, 32 + 2 * i + half); o4 += aj * B[i]; }
.Ldqa_tail:
	s_waitcnt lgkmcnt(0)
	v_mov_b32_e32 v160, 0
	v_mov_b32_e32 v161, 0
	v_mov_b32_e32 v162, 0
	v_mov_b32_e32 v163, 0
	v_mov_b32_e32 v164, 0
	v_mov_b32_e32 v165, 0
	v_mov_b32_e32 v166, 0
	v_mov_b32_e32 v167, 0
	ds_bpermute_b32 v168, v188, v186 offset:0
	ds_bpermute_b32 v170, v188, v186 offset:4
	ds_bpermute_b32 v172, v188, v186 offset:8
	ds_bpermute_b32 v174, v188, v186 offset:12
	s_waitcnt vmcnt(31) lgkmcnt(3)
	v_pk_fma_f32 v[160:161], v[4:5], v[168:169], v[160:161] op_sel_hi:[1,0,1]
	v_pk_fma_f32 v[162:163], v[6:7], v[168:169], v[162:163] op_sel_hi:[1,0,1]
	ds_bpermute_b32 v168, v188, v186 offset:16
	s_waitcnt vmcnt(30) lgkmcnt(3)
	v_pk_fma_f32 v[164:165], v[8:9], v[170:171], v[164:165] op_sel_hi:[1,0,1]
	v_pk_fma_f32 v[166:167], v[10:11], v[170:171], v[166:167] op_sel_hi:[1,0,1]
	ds_bpermute_b32 v170, v188, v186 offset:20
	s_waitcnt vmcnt(29) lgkmcnt(3)
	v_pk_fma_f32 v[160:161], v[12:13], v[172:173], v[160:161] op_sel_hi:[1,0,1]
	v_pk_fma_f32 v[162:163], v[14:15], v[172:173], v[162:163] op_sel_hi:[1,0,1]
	ds_bpermute_b32 v172, v188, v186 offset:24
	s_waitcnt vmcnt(28) lgkmcnt(3)
	v_pk_fma_f32 v[164:165], v[16:17], v[174:175], v[164:165] op_sel_hi:[1,0,1]
	v_pk_fma_f32 v[166:167], v[18:19], v[174:175], v[166:167] op_sel_hi:[1,0,1]
	ds_bpermute_b32 v174, v188, v186 offset:28
	s_waitcnt vmcnt(27) lgkmcnt(3)
	v_pk_fma_f32 v[160:161], v[20:21], v[168:169], v[160:161] op_sel_hi:[1,0,1]
	v_pk_fma_f32 v[162:163], v[22:23], v[168:169], v[162:163] op_sel_hi:[1,0,1]
	ds_bpermute_b32 v168, v188, v186 offset:32
	s_waitcnt vmcnt(26) lgkmcnt(3)
	v_pk_fma_f32 v[164:165], v[24:25], v[170:171], v[164:165] op_sel_hi:[1,0,1]
	v_pk_fma_f32 v[166:167], v[26:27], v[170:171], v[166:167] op_sel_hi:[1,0,1]
	ds_bpermute_b32 v170, v188, v186 offset:36
	s_waitcnt vmcnt(25) lgkmcnt(3)
	v_pk_fma_f32 v[160:161], v[28:29], v[172:173], v[160:161] op_sel_hi:[1,0,1]
	v_pk_fma_f32 v[162:163], v[30:31], v[172:173], v[162:163] op_sel_hi:[1,0,1]
	ds_bpermute_b32 v172, v188, v186 offset:40
	s_waitcnt vmcnt(24) lgkmcnt(3)
	v_pk_fma_f32 v[164:165], v[32:33], v[174:175], v[164:165] op_sel_hi:[1,0,1]
	v_pk_fma_f32 v[166:167], v[34:35], v[174:175], v[166:167] op_sel_hi:[1,0,1]
	ds_bpermute_b32 v174, v188, v186 offset:44
	s_waitcnt vmcnt(23) lgkmcnt(3)
	v_pk_fma_f32 v[160:161], v[36:37], v[168:169], v[160:161] op_sel_hi:[1,0,1]
	v_pk_fma_f32 v[162:163], v[38:39], v[168:169], v[162:163] op_sel_hi:[1,0,1]
	ds_bpermute_b32 v168, v188, v186 offset:48
	s_waitcnt vmcnt(22) lgkmcnt(3)
	v_pk_fma_f32 v[164:165], v[40:41], v[170:171], v[164:165] op_sel_hi:[1,0,1]
	v_pk_fma_f32 v[166:167], v[42:43], v[170:171], v[166:167] op_sel_hi:[1,0,1]
	ds_bpermute_b32 v170, v188, v186 offset:52
	s_waitcnt vmcnt(21) lgkmcnt(3)
	v_pk_fma_f32 v[160:161], v[44:45], v[172:173], v[160:161] op_sel_hi:[1,0,1]
	v_pk_fma_f32 v[162:163], v[46:47], v[172:173], v[162:163] op_sel_hi:[1,0,1]
	ds_bpermute_b32 v172, v188, v186 offset:56
	s_waitcnt vmcnt(20) lgkmcnt(3)
	v_pk_fma_f32 v[164:165], v[48:49], v[174:175], v[164:165] op_sel_hi:[1,0,1]
	v_pk_fma_f32 v[166:167], v[50:51], v[174:175], v[166:167] op_sel_hi:[1,0,1]
	ds_bpermute_b32 v174, v188, v186 offset:60
	s_waitcnt vmcnt(19) lgkmcnt(3)
	v_pk_fma_f32 v[160:161], v[52:53], v[168:169], v[160:161] op_sel_hi:[1,0,1]
	v_pk_fma_f32 v[162:163], v[54:55], v[168:169], v[162:163] op_sel_hi:[1,0,1]
	ds_bpermute_b32 v168, v188, v186 offset:64
	s_waitcnt vmcnt(18) lgkmcnt(3)
	v_pk_fma_f32 v[164:165], v[56:57], v[170:171], v[164:165] op_sel_hi:[1,0,1]
	v_pk_fma_f32 v[166:167], v[58:59], v[170:171], v[166:167] op_sel_hi:[1,0,1]
	ds_bpermute_b32 v170, v188, v186 offset:68
	s_waitcnt vmcnt(17) lgkmcnt(3)
	v_pk_fma_f32 v[160:161], v[60:61], v[172:173], v[160:161] op_sel_hi:[1,0,1]
	v_pk_fma_f32 v[162:163], v[62:63], v[172:173], v[162:163] op_sel_hi:[1,0,1]
	ds_bpermute_b32 v172, v188, v186 offset:72
	s_waitcnt vmcnt(16) lgkmcnt(3)
	v_pk_fma_f32 v[164:165], v[64:65], v[174:175], v[164:165] op_sel_hi:[1,0,1]
	v_pk_fma_f32 v[166:167], v[66:67], v[174:175], v[166:167] op_sel_hi:[1,0,1]
	ds_bpermute_b32 v174, v188, v186 offset:76
	s_waitcnt vmcnt(15) lgkmcnt(3)
	v_pk_fma_f32 v[160:161], v[68:69], v[168:169], v[160:161] op_sel_hi:[1,0,1]
	v_pk_fma_f32 v[162:163], v[70:71], v[168:169], v[162:163] op_sel_hi:[1,0,1]
	ds_bpermute_b32 v168, v188, v186 offset:80
	s_waitcnt vmcnt(14) lgkmcnt(3)
; __device__ __forceinline__ void sb_decode_stream(Frame& F, unsigned* qctr, int base, int limit) {
;     ...
;         for (int i = 0; i < 16; ++i) { const float aj = __shfl(a, 32 + 2 * i + half); o4 += aj * B[i]; }
; #pragma unroll
;         for (int i = 0; i < 16; ++i) B[i] = __builtin_nontemporal_load((const f32x4*)(CK + cbn + (size_t)(32 + 2 * i) * stepn));
;         o4.x += __shfl_xor(o4.x, 32); o4.y += __shfl_xor(o4.y, 32); o4.z += __shfl_xor(o4.z, 32); o4.w += __shfl_xor(o4.w, 32);
;         float* P = SSP(S_PART) + ((size_t)bh * DSEG + blk) * DPART;
;         if (half == 0) *(f32x4*)(P + 4 * l32) = o4; if (lane == 0) P[128] = tot;
;         if (!more) break;
; __global__ void __launch_bounds__(NWAVES * 64, 2) hymba_fwd(Args args) {
;     ...
;         { unsigned* pq = F.ctl + CW_QUEUE + 128; int cur = dq_first(F, pq), par = 0;
;           while (cur < NB * NH * NCHUNK) {
;               unsigned nxt = 0; if (F.tid == 64) nxt = __hip_atomic_fetch_add(pq, 1u, __ATOMIC_RELAXED, __HIP_MEMORY_SCOPE_AGENT);
	v_pk_fma_f32 v[164:165], v[72:73], v[170:171], v[164:165] op_sel_hi:[1,0,1]
	v_pk_fma_f32 v[166:167], v[74:75], v[170:171], v[166:167] op_sel_hi:[1,0,1]
	ds_bpermute_b32 v170, v188, v186 offset:84
	s_waitcnt vmcnt(13) lgkmcnt(3)
	v_pk_fma_f32 v[160:161], v[76:77], v[172:173], v[160:161] op_sel_hi:[1,0,1]
	v_pk_fma_f32 v[162:163], v[78:79], v[172:173], v[162:163] op_sel_hi:[1,0,1]
	ds_bpermute_b32 v172, v188, v186 offset:88
	s_waitcnt vmcnt(12) lgkmcnt(3)
	v_pk_fma_f32 v[164:165], v[80:81], v[174:175], v[164:165] op_sel_hi:[1,0,1]
	v_pk_fma_f32 v[166:167], v[82:83], v[174:175], v[166:167] op_sel_hi:[1,0,1]
	ds_bpermute_b32 v174, v188, v186 offset:92
	s_waitcnt vmcnt(11) lgkmcnt(3)
	v_pk_fma_f32 v[160:161], v[84:85], v[168:169], v[160:161] op_sel_hi:[1,0,1]
	v_pk_fma_f32 v[162:163], v[86:87], v[168:169], v[162:163] op_sel_hi:[1,0,1]
	ds_bpermute_b32 v168, v188, v186 offset:96
	s_waitcnt vmcnt(10) lgkmcnt(3)
	v_pk_fma_f32 v[164:165], v[88:89], v[170:171], v[164:165] op_sel_hi:[1,0,1]
	v_pk_fma_f32 v[166:167], v[90:91], v[170:171], v[166:167] op_sel_hi:[1,0,1]
	ds_bpermute_b32 v170, v188, v186 offset:100
	s_waitcnt vmcnt(9) lgkmcnt(3)
	v_pk_fma_f32 v[160:161], v[92:93], v[172:173], v[160:161] op_sel_hi:[1,0,1]
	v_pk_fma_f32 v[162:163], v[94:95], v[172:173], v[162:163] op_sel_hi:[1,0,1]
	ds_bpermute_b32 v172, v188, v186 offset:104
	s_waitcnt vmcnt(8) lgkmcnt(3)
	v_pk_fma_f32 v[164:165], v[96:97], v[174:175], v[164:165] op_sel_hi:[1,0,1]
	v_pk_fma_f32 v[166:167], v[98:99], v[174:175], v[166:167] op_sel_hi:[1,0,1]
	ds_bpermute_b32 v174, v188, v186 offset:108
	s_waitcnt vmcnt(7) lgkmcnt(3)
	v_pk_fma_f32 v[160:161], v[100:101], v[168:169], v[160:161] op_sel_hi:[1,0,1]
	v_pk_fma_f32 v[162:163], v[102:103], v[168:169], v[162:163] op_sel_hi:[1,0,1]
	ds_bpermute_b32 v168, v188, v186 offset:112
	s_waitcnt vmcnt(6) lgkmcnt(3)
	v_pk_fma_f32 v[164:165], v[104:105], v[170:171], v[164:165] op_sel_hi:[1,0,1]
	v_pk_fma_f32 v[166:167], v[106:107], v[170:171], v[166:167] op_sel_hi:[1,0,1]
	ds_bpermute_b32 v170, v188, v186 offset:116
	s_waitcnt vmcnt(5) lgkmcnt(3)
	v_pk_fma_f32 v[160:161], v[108:109], v[172:173], v[160:161] op_sel_hi:[1,0,1]
	v_pk_fma_f32 v[162:163], v[110:111], v[172:173], v[162:163] op_sel_hi:[1,0,1]
	ds_bpermute_b32 v172, v188, v186 offset:120
	s_waitcnt vmcnt(4) lgkmcnt(3)
	v_pk_fma_f32 v[164:165], v[112:113], v[174:175], v[164:165] op_sel_hi:[1,0,1]
	v_pk_fma_f32 v[166:167], v[114:115], v[174:175], v[166:167] op_sel_hi:[1,0,1]
	ds_bpermute_b32 v174, v188, v186 offset:124
	s_waitcnt vmcnt(3) lgkmcnt(3)
	v_pk_fma_f32 v[160:161], v[116:117], v[168:169], v[160:161] op_sel_hi:[1,0,1]
	v_pk_fma_f32 v[162:163], v[118:119], v[168:169], v[162:163] op_sel_hi:[1,0,1]
	s_waitcnt vmcnt(2) lgkmcnt(2)
	v_pk_fma_f32 v[164:165], v[120:121], v[170:171], v[164:165] op_sel_hi:[1,0,1]
	v_pk_fma_f32 v[166:167], v[122:123], v[170:171], v[166:167] op_sel_hi:[1,0,1]
	s_waitcnt vmcnt(1) lgkmcnt(1)
	v_pk_fma_f32 v[160:161], v[124:125], v[172:173], v[160:161] op_sel_hi:[1,0,1]
	v_pk_fma_f32 v[162:163], v[126:127], v[172:173], v[162:163] op_sel_hi:[1,0,1]
	s_waitcnt vmcnt(0) lgkmcnt(0)
	v_pk_fma_f32 v[164:165], v[128:129], v[174:175], v[164:165] op_sel_hi:[1,0,1]
	v_pk_fma_f32 v[166:167], v[130:131], v[174:175], v[166:167] op_sel_hi:[1,0,1]
	v_pk_add_f32 v[160:161], v[160:161], v[164:165]
	v_pk_add_f32 v[162:163], v[162:163], v[166:167]
	v_mov_b32_e32 v164, v160
	v_mov_b32_e32 v165, v161
	v_mov_b32_e32 v166, v162
	v_mov_b32_e32 v167, v163
	v_permlane32_swap_b32_e32 v160, v164
	v_permlane32_swap_b32_e32 v161, v165
	v_permlane32_swap_b32_e32 v162, v166
	v_permlane32_swap_b32_e32 v163, v167
	v_pk_add_f32 v[160:161], v[160:161], v[164:165]
	v_pk_add_f32 v[162:163], v[162:163], v[166:167]
	s_mov_b32 exec_hi, 0
	global_store_dwordx4 v193, v[160:163], s[70:71]
	s_mov_b32 exec_lo, 1
	global_store_dword v189, v183, s[70:71] offset:512
	s_mov_b64 exec, -1
.Ldqa_exit:
.LBB0_1132:
	s_add_u32 s10, s26, 0x1200
	s_addc_u32 s11, s27, 0
	v_cmp_eq_u32_e64 s[6:7], 64, v0
	s_and_saveexec_b64 s[8:9], s[6:7]
	s_cbranch_execz .LBB0_1136
	s_mov_b64 s[14:15], exec
	v_mbcnt_lo_u32_b32 v1, s14, 0
	v_mbcnt_hi_u32_b32 v1, s15, v1
	v_cmp_eq_u32_e32 vcc, 0, v1
	s_and_saveexec_b64 s[12:13], vcc
	s_cbranch_execz .LBB0_1135
	s_bcnt1_i32_b64 s2, s[14:15]
	s_waitcnt vmcnt(32)
	v_mov_b32_e32 v2, 0
	v_mov_b32_e32 v3, s2
	global_atomic_add v2, v2, v3, s[10:11] sc0

; __device__ __forceinline__ void sb_decode_stream(Frame& F, unsigned* qctr, int base, int limit) {
;     const float* CK = kin(2); const float* CV = kin(3); const int* PT = (const int*)kin(4);
;     int lane = F.lane; asm volatile("" : "+v"(lane));
;     const int half = lane >> 5, l32 = lane & 31;
;     const float k1 = SB_SCALE * 1.4426950408889634f;
;     const size_t lo = (size_t)half * (NH * HD) + 4 * l32;
;     int it;
;     { const unsigned v = __hip_atomic_fetch_add(qctr, 1u, __ATOMIC_RELAXED, __HIP_MEMORY_SCOPE_AGENT);
;       it = (int)(__builtin_amdgcn_readfirstlane(v) >> 6); if (it >= limit) return; it += base; }
; __global__ void __launch_bounds__(NWAVES * 64, 2) hymba_fwd(Args args) {
;     ...
;         if (!streamer) sb_decode_stream(F, F.ctl + CW_QUEUE, 0, DEC_Q2);
.LBB0_1294:
	s_load_dwordx2 s[50:51], s[0:1], 0x10
	s_load_dwordx2 s[52:53], s[0:1], 0x18
	s_load_dwordx2 s[54:55], s[0:1], 0x20
	s_load_dwordx2 s[56:57], s[0:1], 0x60
	s_add_u32 s58, s26, 0x1000
	s_addc_u32 s59, s27, 0
	s_add_u32 s60, s26, 0x2ff18000
	s_addc_u32 s61, s27, 0
	s_add_u32 s62, s26, 0x2ff70400
	s_addc_u32 s63, s27, 0
	s_mov_b32 s76, 0xcccccccc
	s_mov_b32 s77, 0xcccccccc
	s_mov_b32 s78, 0xaaaaaaaa
	s_mov_b32 s79, 0xaaaaaaaa
	v_and_b32_e32 v193, 31, v199
	v_lshrrev_b32_e32 v188, 5, v199
	v_lshlrev_b32_e32 v193, 4, v193
	v_lshl_add_u32 v187, v188, 12, v193
	v_lshlrev_b32_e32 v188, 7, v188
	v_mov_b32_e32 v189, 0
	v_mov_b32_e32 v190, 64
	v_mov_b32_e32 v190, 0x200
	s_mov_b32 s37, 0x251e0
	s_cmp_eq_u32 s94, 0
	s_cbranch_scc0 .Ldqb_pro
	s_mov_b64 exec, 1
	global_atomic_add v191, v189, v190, s[58:59] sc0
	s_mov_b64 exec, -1

; __device__ __forceinline__ void gdn_prep_sample(Frame& F) {
;     const float* PR = SSP(S_PROJ); const float* hist = kin(5); const float* cw = kin(14);
;     const int gt = F.bid * 512 + F.tid, NT = F.G * 512;
;     for (int i = gt; i < MS * SBW; i += NT) { const int b = i >> 10, c = i & 1023; F.out[OUT_KS + i] = PR[(size_t)b * IN_COLS + O_SB_K + c]; F.out[OUT_VS + i] = PR[(size_t)b * IN_COLS + O_SB_V + c]; }
.Ldqb_exit:
.LBB0_1306:
	s_mov_b32 s2, 40
	s_load_dwordx2 s[10:11], s[0:1], s2 offset:0x0
	s_movk_i32 s2, 0x70
	s_load_dwordx2 s[8:9], s[0:1], s2 offset:0x0
	s_waitcnt vmcnt(32)
	v_lshl_or_b32 v4, s96, 9, v0
	s_movk_i32 s2, 0x2000
	s_lshl_b32 s6, s34, 9
	v_cmp_gt_i32_e32 vcc, s2, v4
	v_ashrrev_i32_e32 v5, 31, v4
	s_and_saveexec_b64 s[12:13], vcc
	s_cbranch_execz .LBB0_1309
	v_lshl_add_u64 v[2:3], v[4:5], 2, s[24:25]
	s_mov_b64 s[2:3], 0x8137800
	s_ashr_i32 s7, s6, 31
	v_lshl_add_u64 v[2:3], v[2:3], 0, s[2:3]
	s_lshl_b64 s[14:15], s[6:7], 2
	s_mov_b64 s[16:17], 0
	s_waitcnt vmcnt(0)
	v_mov_b32_e32 v7, 0
	s_movk_i32 s2, 0x1fff
	v_mov_b32_e32 v1, v4

; __device__ __forceinline__ void sb_decode_stream(Frame& F, unsigned* qctr, int base, int limit) {
;     const float* CK = kin(2); const float* CV = kin(3); const int* PT = (const int*)kin(4);
;     int lane = F.lane; asm volatile("" : "+v"(lane));
;     const int half = lane >> 5, l32 = lane & 31;
;     const float k1 = SB_SCALE * 1.4426950408889634f;
;     const size_t lo = (size_t)half * (NH * HD) + 4 * l32;
;     int it;
;     { const unsigned v = __hip_atomic_fetch_add(qctr, 1u, __ATOMIC_RELAXED, __HIP_MEMORY_SCOPE_AGENT);
;       it = (int)(__builtin_amdgcn_readfirstlane(v) >> 6); if (it >= limit) return; it += base; }
; __device__ __forceinline__ void p2_mixers(Frame& F, unsigned* qctr) {
;     ...
;     const bool streamer = (F.bid >= NB * NH) && (((F.bid >> 3) - 2) % 5 < 2);
;     if (streamer) sb_decode_stream(F, qctr + 64, DEC_Q2, DEC_ITEMS - DEC_Q2);
.LBB0_1408:
	s_lshr_b32 s2, s96, 3
	s_add_i32 s2, s2, -2
	s_mul_hi_u32 s3, s2, 0xcccccccd
	s_lshr_b32 s3, s3, 2
	s_mul_i32 s3, s3, 5
	s_sub_i32 s2, s2, s3
	s_cmp_gt_u32 s2, 1
	s_cselect_b64 s[6:7], -1, 0
	s_add_u32 s38, s26, 0x1100
	s_addc_u32 s39, s27, 0
	s_add_u32 s3, s26, 0x2ff18000
	s_addc_u32 s4, s27, 0
	s_add_u32 s5, s26, 0x2ff70400
	s_addc_u32 s23, s27, 0
	s_or_b64 s[6:7], s[10:11], s[6:7]
	s_andn2_b64 vcc, exec, s[6:7]
	s_cbranch_vccz .LBB0_1420
	s_load_dwordx2 s[50:51], s[0:1], 0x10
	s_load_dwordx2 s[52:53], s[0:1], 0x18
	s_load_dwordx2 s[54:55], s[0:1], 0x20
	s_load_dwordx2 s[56:57], s[0:1], 0x60
	s_add_u32 s58, s26, 0x1100
	s_addc_u32 s59, s27, 0
	s_add_u32 s60, s26, 0x2ff18000
	s_addc_u32 s61, s27, 0
	s_add_u32 s62, s26, 0x2ff70400
	s_addc_u32 s63, s27, 0
	s_mov_b32 s76, 0xcccccccc
	s_mov_b32 s77, 0xcccccccc
	s_mov_b32 s78, 0xaaaaaaaa
	s_mov_b32 s79, 0xaaaaaaaa
	v_and_b32_e32 v193, 31, v199
	v_lshrrev_b32_e32 v188, 5, v199
	v_lshlrev_b32_e32 v193, 4, v193
	v_lshl_add_u32 v187, v188, 12, v193
	v_lshlrev_b32_e32 v188, 7, v188
	v_mov_b32_e32 v189, 0
	v_mov_b32_e32 v190, 64
	v_mov_b32_e32 v190, 0x200
	s_mov_b32 s37, 0x251e0
	s_cmp_eq_u32 s94, 0
	s_cbranch_scc0 .Ldqc_pro
	s_mov_b64 exec, 1
	global_atomic_add v191, v189, v190, s[58:59] sc0
	s_mov_b64 exec, -1

; __device__ __forceinline__ void sb_decode_stream(Frame& F, unsigned* qctr, int base, int limit) {
;     ...
;     { const unsigned v = __hip_atomic_fetch_add(qctr, 1u, __ATOMIC_RELAXED, __HIP_MEMORY_SCOPE_AGENT);
;       it = (int)(__builtin_amdgcn_readfirstlane(v) >> 6); if (it >= limit) return; it += base; }
;     f32x4 A[16], B[16], q4;
;     size_t cb;
;     { const int b = it >> 11, h = it & 7, p0 = ((it >> 3) & 255) * 64;
;       const int page = PT[b * NPAGES + (p0 >> 7)];
;       cb = (((size_t)page * PAGE + (p0 & 127)) * NH + h) * HD + lo;
;       q4 = *(const f32x4*)(SSP(S_PROJ) + (size_t)b * IN_COLS + h * HD + 4 * l32);
; #pragma unroll
;       for (int i = 0; i < 16; ++i) A[i] = __builtin_nontemporal_load((const f32x4*)(CK + cb + (size_t)(2 * i) * (NH * HD)));
; #pragma unroll
;       for (int i = 0; i < 16; ++i) B[i] = __builtin_nontemporal_load((const f32x4*)(CK + cb + (size_t)(32 + 2 * i) * (NH * HD))); }
.Ldqc_sh1:
	s_barrier
	ds_read_b32 v201, v200
	s_xor_b32 s37, s37, 4
	s_waitcnt lgkmcnt(0)
	v_readfirstlane_b32 s2, v201
	s_nop 0
	s_lshr_b32 s72, s2, 6
	s_cmp_ge_u32 s72, 0x2800
	s_cbranch_scc1 .Ldqc_exit
	s_add_u32 s72, s72, s94
	s_min_u32 s72, s72, 0x27ff
	s_mov_b32 s74, s72
	s_mov_b32 s75, 0
	s_add_u32 s72, s72, 0x1800
	s_waitcnt lgkmcnt(0)
	s_lshr_b32 s6, s72, 11
	s_and_b32 s7, s72, 7
	s_bfe_u32 s8, s72, 0x80003
	s_lshl_b32 s9, s6, 7
	s_lshr_b32 s10, s8, 1
	s_or_b32 s9, s9, s10
	s_lshl_b32 s9, s9, 2
	s_lshl_b32 s10, s7, 2
	s_load_dword s29, s[54:55], s9
	s_load_dword s30, s[56:57], s10
	s_waitcnt lgkmcnt(0)
	s_mov_b32 s12, s29
	s_mov_b32 s13, 0
	s_lshl_b64 s[12:13], s[12:13], 19
	s_and_b32 s14, s8, 1
	s_lshl_b32 s14, s14, 18
	s_lshl_b32 s15, s7, 9
	s_or_b32 s14, s14, s15
	s_or_b32 s80, s12, s14
	s_mov_b32 s81, s13
	s_add_u32 s64, s50, s80
	s_addc_u32 s65, s51, s81
	s_mul_i32 s16, s6, 0x7040
	s_add_u32 s16, s16, s15
	s_add_u32 s16, s60, s16
	s_addc_u32 s17, s61, 0
	global_load_dwordx4 v[156:159], v193, s[16:17]
	global_load_dwordx4 v[4:7], v187, s[64:65] nt
	s_add_u32 s64, s64, 0x2000
	s_addc_u32 s65, s65, 0
	global_load_dwordx4 v[8:11], v187, s[64:65] nt
	s_add_u32 s64, s64, 0x2000
	s_addc_u32 s65, s65, 0
	global_load_dwordx4 v[12:15], v187, s[64:65] nt
	s_add_u32 s64, s64, 0x2000
	s_addc_u32 s65, s65, 0
	global_load_dwordx4 v[16:19], v187, s[64:65] nt
	s_add_u32 s64, s64, 0x2000
	s_addc_u32 s65, s65, 0
	global_load_dwordx4 v[20:23], v187, s[64:65] nt
	s_add_u32 s64, s64, 0x2000
	s_addc_u32 s65, s65, 0
	global_load_dwordx4 v[24:27], v187, s[64:65] nt
	s_add_u32 s64, s64, 0x2000
	s_addc_u32 s65, s65, 0
	global_load_dwordx4 v[28:31], v187, s[64:65] nt
	s_add_u32 s64, s64, 0x2000
	s_addc_u32 s65, s65, 0
	global_load_dwordx4 v[32:35], v187, s[64:65] nt
	s_add_u32 s64, s64, 0x2000
	s_addc_u32 s65, s65, 0
	global_load_dwordx4 v[36:39], v187, s[64:65] nt
	s_add_u32 s64, s64, 0x2000
	s_addc_u32 s65, s65, 0
	global_load_dwordx4 v[40:43], v187, s[64:65] nt
	s_add_u32 s64, s64, 0x2000
	s_addc_u32 s65, s65, 0
	global_load_dwordx4 v[44:47], v187, s[64:65] nt
	s_add_u32 s64, s64, 0x2000
	s_addc_u32 s65, s65, 0
	global_load_dwordx4 v[48:51], v187, s[64:65] nt
	s_add_u32 s64, s64, 0x2000
	s_addc_u32 s65, s65, 0
	global_load_dwordx4 v[52:55], v187, s[64:65] nt
	s_add_u32 s64, s64, 0x2000
	s_addc_u32 s65, s65, 0
	global_load_dwordx4 v[56:59], v187, s[64:65] nt
	s_add_u32 s64, s64, 0x2000
	s_addc_u32 s65, s65, 0
	global_load_dwordx4 v[60:63], v187, s[64:65] nt
	s_add_u32 s64, s64, 0x2000
	s_addc_u32 s65, s65, 0
	global_load_dwordx4 v[64:67], v187, s[64:65] nt
	s_add_u32 s64, s64, 0x2000
	s_addc_u32 s65, s65, 0
	global_load_dwordx4 v[68:71], v187, s[64:65] nt
	s_add_u32 s64, s64, 0x2000
	s_addc_u32 s65, s65, 0
	global_load_dwordx4 v[72:75], v187, s[64:65] nt
	s_add_u32 s64, s64, 0x2000
	s_addc_u32 s65, s65, 0
	global_load_dwordx4 v[76:79], v187, s[64:65] nt
	s_add_u32 s64, s64, 0x2000
	s_addc_u32 s65, s65, 0
	global_load_dwordx4 v[80:83], v187, s[64:65] nt
	s_add_u32 s64, s64, 0x2000
	s_addc_u32 s65, s65, 0
	global_load_dwordx4 v[84:87], v187, s[64:65] nt
	s_add_u32 s64, s64, 0x2000
	s_addc_u32 s65, s65, 0
	global_load_dwordx4 v[88:91], v187, s[64:65] nt
	s_add_u32 s64, s64, 0x2000
	s_addc_u32 s65, s65, 0
	global_load_dwordx4 v[92:95], v187, s[64:65] nt
	s_add_u32 s64, s64, 0x2000
	s_addc_u32 s65, s65, 0
	global_load_dwordx4 v[96:99], v187, s[64:65] nt
	s_add_u32 s64, s64, 0x2000
	s_addc_u32 s65, s65, 0
	global_load_dwordx4 v[100:103], v187, s[64:65] nt
	s_add_u32 s64, s64, 0x2000
	s_addc_u32 s65, s65, 0
	global_load_dwordx4 v[104:107], v187, s[64:65] nt
	s_add_u32 s64, s64, 0x2000
	s_addc_u32 s65, s65, 0
	global_load_dwordx4 v[108:111], v187, s[64:65] nt
	s_add_u32 s64, s64, 0x2000
	s_addc_u32 s65, s65, 0
	global_load_dwordx4 v[112:115], v187, s[64:65] nt
	s_add_u32 s64, s64, 0x2000
	s_addc_u32 s65, s65, 0
	global_load_dwordx4 v[116:119], v187, s[64:65] nt
	s_add_u32 s64, s64, 0x2000
	s_addc_u32 s65, s65, 0
	global_load_dwordx4 v[120:123], v187, s[64:65] nt
	s_add_u32 s64, s64, 0x2000
	s_addc_u32 s65, s65, 0
	global_load_dwordx4 v[124:127], v187, s[64:65] nt
	s_add_u32 s64, s64, 0x2000
	s_addc_u32 s65, s65, 0
	global_load_dwordx4 v[128:131], v187, s[64:65] nt
	s_add_u32 s64, s64, 0x2000
	s_addc_u32 s65, s65, 0
	global_load_dword v194, v189, s[58:59]
	global_load_dword v195, v189, s[58:59]

; __device__ __forceinline__ void sb_decode_stream(Frame& F, unsigned* qctr, int base, int limit) {
;     ...
;         const int bh = ((it >> 11) << 3) | (it & 7), blk = (it >> 3) & 255, h = it & 7;
;         const unsigned vn = __hip_atomic_fetch_add(qctr, 1u, __ATOMIC_RELAXED, __HIP_MEMORY_SCOPE_AGENT);
;         const float k2 = kin(12)[h] * 1.4426950408889634f;
;         int zi = 0;
;     ...
;         DEC_SCORES(A, 0);
; #pragma unroll
;         for (int i = 0; i < 16; ++i) A[i] = __builtin_nontemporal_load((const f32x4*)(CV + cb + (size_t)(2 * i) * (NH * HD)));
;         DEC_SCORES(B, 1);
;     ...
; #pragma unroll
;         for (int i = 0; i < 16; ++i) B[i] = __builtin_nontemporal_load((const f32x4*)(CV + cb + (size_t)(32 + 2 * i) * (NH * HD)));
;         const float z = __builtin_bit_cast(float, zi);
;         const float e = __builtin_amdgcn_exp2f(-(z * k1 + k2));
;         const float be = __builtin_amdgcn_rcpf(1.0f + e), m = 1.0f - be;
;         float s = m;
; #pragma unroll
;         for (int o = 1; o < 64; o <<= 1) { const float t = __shfl_down(s, o); if (lane + o < 64) s *= t; }
;         const float tot = __shfl(s, 0);
;         const float sx = __shfl_down(s, 1);
;         const float a = be * (lane < 63 ? sx : 1.0f);
;         int itn = (int)(__builtin_amdgcn_readfirstlane(vn) >> 6); const bool more = itn < limit; itn = more ? itn + base : it;
;         const int bn = itn >> 11, hn = itn & 7, p0n = ((itn >> 3) & 255) * 64;
;         const int pagen = PT[bn * NPAGES + (p0n >> 7)];
;         const size_t cbn = (((size_t)pagen * PAGE + (p0n & 127)) * NH + hn) * HD + lo;
;         const size_t stepn = more ? (size_t)(NH * HD) : 0;
.Ldqc_sh2:
	s_barrier
	ds_read_b32 v201, v200
	s_xor_b32 s37, s37, 4
	s_waitcnt lgkmcnt(0)
	v_readfirstlane_b32 s2, v201
	s_nop 0
	s_lshr_b32 s73, s2, 6
	s_cmp_lt_u32 s73, 0x2800
	s_cselect_b32 s31, 1, 0
	s_add_u32 s73, s73, s94
	s_min_u32 s73, s73, 0x27ff
	s_add_u32 s73, s73, 0x1800
	s_cmp_eq_u32 s31, 1
	s_cselect_b32 s73, s73, s72
	s_lshr_b32 s6, s73, 11
	s_and_b32 s7, s73, 7
	s_bfe_u32 s8, s73, 0x80003
	s_lshl_b32 s9, s6, 7
	s_lshr_b32 s10, s8, 1
	s_or_b32 s9, s9, s10
	s_lshl_b32 s9, s9, 2
	s_lshl_b32 s10, s7, 2
	s_load_dword s29, s[54:55], s9
	s_load_dword s30, s[56:57], s10
	v_add_f32_dpp v132, v132, v132 row_ror:8 row_mask:0xf bank_mask:0x3
	v_add_f32_dpp v133, v133, v133 row_ror:8 row_mask:0xf bank_mask:0x3
	v_add_f32_dpp v134, v134, v134 row_ror:8 row_mask:0xf bank_mask:0x3
	v_add_f32_dpp v135, v135, v135 row_ror:8 row_mask:0xf bank_mask:0x3
	v_add_f32_dpp v136, v136, v136 row_ror:8 row_mask:0xf bank_mask:0x3
	v_add_f32_dpp v137, v137, v137 row_ror:8 row_mask:0xf bank_mask:0x3
	v_add_f32_dpp v138, v138, v138 row_ror:8 row_mask:0xf bank_mask:0x3
	v_add_f32_dpp v139, v139, v139 row_ror:8 row_mask:0xf bank_mask:0x3
	v_add_f32_dpp v132, v140, v140 row_ror:8 row_mask:0xf bank_mask:0xc
	v_add_f32_dpp v133, v141, v141 row_ror:8 row_mask:0xf bank_mask:0xc
	v_add_f32_dpp v134, v142, v142 row_ror:8 row_mask:0xf bank_mask:0xc
	v_add_f32_dpp v135, v143, v143 row_ror:8 row_mask:0xf bank_mask:0xc
	v_add_f32_dpp v136, v144, v144 row_ror:8 row_mask:0xf bank_mask:0xc
	v_add_f32_dpp v137, v145, v145 row_ror:8 row_mask:0xf bank_mask:0xc
	v_add_f32_dpp v138, v146, v146 row_ror:8 row_mask:0xf bank_mask:0xc
	v_add_f32_dpp v139, v147, v147 row_ror:8 row_mask:0xf bank_mask:0xc
	v_add_f32_dpp v132, v132, v132 row_ror:12 row_mask:0xf bank_mask:0x5
	v_add_f32_dpp v133, v133, v133 row_ror:12 row_mask:0xf bank_mask:0x5
	v_add_f32_dpp v134, v134, v134 row_ror:12 row_mask:0xf bank_mask:0x5
	v_add_f32_dpp v135, v135, v135 row_ror:12 row_mask:0xf bank_mask:0x5
	v_add_f32_dpp v132, v136, v136 row_ror:4 row_mask:0xf bank_mask:0xa
	v_add_f32_dpp v133, v137, v137 row_ror:4 row_mask:0xf bank_mask:0xa
	v_add_f32_dpp v134, v138, v138 row_ror:4 row_mask:0xf bank_mask:0xa
	v_add_f32_dpp v135, v139, v139 row_ror:4 row_mask:0xf bank_mask:0xa
	v_add_f32_dpp v140, v132, v132 quad_perm:[2,3,0,1] row_mask:0xf bank_mask:0xf
	v_add_f32_dpp v142, v134, v134 quad_perm:[2,3,0,1] row_mask:0xf bank_mask:0xf
	v_add_f32_dpp v141, v133, v133 quad_perm:[2,3,0,1] row_mask:0xf bank_mask:0xf
	v_add_f32_dpp v143, v135, v135 quad_perm:[2,3,0,1] row_mask:0xf bank_mask:0xf
	v_cndmask_b32_e64 v132, v140, v142, s[76:77]
	v_cndmask_b32_e64 v133, v141, v143, s[76:77]
	s_nop 0
	v_add_f32_dpp v196, v132, v132 quad_perm:[1,0,3,2] row_mask:0xf bank_mask:0xf
	v_add_f32_dpp v197, v133, v133 quad_perm:[1,0,3,2] row_mask:0xf bank_mask:0xf
	v_cndmask_b32_e64 v177, v196, v197, s[78:79]
	s_nop 1
	v_permlane16_swap_b32_e32 v176, v177
	v_add_f32_e32 v178, v176, v177
	v_mul_f32_e32 v178, 0x3e0293ee, v178
	v_add_f32_e32 v178, v178, v192
	v_exp_f32_e64 v198, -v178
	s_nop 0
	v_add_f32_e32 v198, 1.0, v198
	v_rcp_f32_e32 v179, v198
	s_nop 0
	v_sub_f32_e32 v180, 1.0, v179
	v_mov_b32_e32 v181, v180
	s_nop 1
	v_permlane32_swap_b32_e32 v180, v181
	v_mul_f32_e32 v183, v180, v181
	s_nop 1
	v_mul_f32_dpp v183, v183, v183 row_shl:1 row_mask:0xf bank_mask:0xf
	s_nop 1
	v_mul_f32_dpp v183, v183, v183 row_shl:2 row_mask:0xf bank_mask:0xf
	s_nop 1
	v_mul_f32_dpp v183, v183, v183 row_shl:4 row_mask:0xf bank_mask:0xf
	s_nop 1
	v_mul_f32_dpp v183, v183, v183 row_shl:8 row_mask:0xf bank_mask:0xf
	s_nop 0
	v_readlane_b32 s33, v183, 16
	v_mov_b32_e32 v184, 1.0
	s_nop 0
	v_mov_b32_e32 v185, s33
	s_nop 1
	v_mul_f32_dpp v183, v183, v185 quad_perm:[0,1,2,3] row_mask:0x5 bank_mask:0xf
	v_mov_b32_dpp v184, v185 quad_perm:[0,1,2,3] row_mask:0x5 bank_mask:0xf
	s_nop 1
	v_mov_b32_dpp v184, v183 row_shl:1 row_mask:0xf bank_mask:0xf
	v_mul_f32_e32 v186, v179, v184
	s_nop 1
	v_mul_f32_dpp v186, v186, v181 quad_perm:[0,1,2,3] row_mask:0x3 bank_mask:0xf
	s_cmp_eq_u32 s31, 0
	s_cbranch_scc1 .Ldqc_tail
	s_waitcnt lgkmcnt(0)
	s_mov_b32 s12, s29
	s_mov_b32 s13, 0
	s_lshl_b64 s[12:13], s[12:13], 19
	s_and_b32 s14, s8, 1
	s_lshl_b32 s14, s14, 18
	s_lshl_b32 s15, s7, 9
	s_or_b32 s14, s14, s15
	s_or_b32 s80, s12, s14
	s_mov_b32 s81, s13
	s_add_u32 s64, s50, s80
	s_addc_u32 s65, s51, s81
	s_mul_i32 s16, s6, 0x7040
	s_add_u32 s16, s16, s15
	s_add_u32 s16, s60, s16
	s_addc_u32 s17, s61, 0
	global_load_dwordx4 v[156:159], v193, s[16:17]
	v_mov_b32_e32 v160, 0
	v_mov_b32_e32 v161, 0
	v_mov_b32_e32 v162, 0
	v_mov_b32_e32 v163, 0
	v_mov_b32_e32 v164, 0
	v_mov_b32_e32 v165, 0
	v_mov_b32_e32 v166, 0
	v_mov_b32_e32 v167, 0
	ds_bpermute_b32 v168, v188, v186 offset:0
	ds_bpermute_b32 v170, v188, v186 offset:4
	ds_bpermute_b32 v172, v188, v186 offset:8
	ds_bpermute_b32 v174, v188, v186 offset:12
	s_waitcnt vmcnt(32) lgkmcnt(3)
	v_pk_fma_f32 v[160:161], v[4:5], v[168:169], v[160:161] op_sel_hi:[1,0,1]
	v_pk_fma_f32 v[162:163], v[6:7], v[168:169], v[162:163] op_sel_hi:[1,0,1]
	global_load_dwordx4 v[4:7], v187, s[64:65] nt
	s_add_u32 s64, s64, 0x2000
	s_addc_u32 s65, s65, 0
	ds_bpermute_b32 v168, v188, v186 offset:16
	s_waitcnt vmcnt(32) lgkmcnt(3)
	v_pk_fma_f32 v[164:165], v[8:9], v[170:171], v[164:165] op_sel_hi:[1,0,1]
	v_pk_fma_f32 v[166:167], v[10:11], v[170:171], v[166:167] op_sel_hi:[1,0,1]
	global_load_dwordx4 v[8:11], v187, s[64:65] nt
	s_add_u32 s64, s64, 0x2000
	s_addc_u32 s65, s65, 0
	ds_bpermute_b32 v170, v188, v186 offset:20
	s_waitcnt vmcnt(32) lgkmcnt(3)
; __device__ __forceinline__ void sb_decode_stream(Frame& F, unsigned* qctr, int base, int limit) {
;     ...
;         f32x4 o4 = {0.f, 0.f, 0.f, 0.f};
; #pragma unroll
;         for (int i = 0; i < 16; ++i) { const float aj = __shfl(a, 2 * i + half); o4 += aj * A[i]; }
;         const f32x4 q4n = *(const f32x4*)(SSP(S_PROJ) + (size_t)bn * IN_COLS + hn * HD + 4 * l32);
; #pragma unroll
;         for (int i = 0; i < 16; ++i) A[i] = __builtin_nontemporal_load((const f32x4*)(CK + cbn + (size_t)(2 * i) * stepn));
; #pragma unroll
;         for (int i = 0; i < 16; ++i) { const float aj = __shfl(a, 32 + 2 * i + half); o4 += aj * B[i]; }
	v_pk_fma_f32 v[160:161], v[12:13], v[172:173], v[160:161] op_sel_hi:[1,0,1]
	v_pk_fma_f32 v[162:163], v[14:15], v[172:173], v[162:163] op_sel_hi:[1,0,1]
	global_load_dwordx4 v[12:15], v187, s[64:65] nt
	s_add_u32 s64, s64, 0x2000
	s_addc_u32 s65, s65, 0
	ds_bpermute_b32 v172, v188, v186 offset:24
	s_waitcnt vmcnt(32) lgkmcnt(3)
	v_pk_fma_f32 v[164:165], v[16:17], v[174:175], v[164:165] op_sel_hi:[1,0,1]
	v_pk_fma_f32 v[166:167], v[18:19], v[174:175], v[166:167] op_sel_hi:[1,0,1]
	global_load_dwordx4 v[16:19], v187, s[64:65] nt
	s_add_u32 s64, s64, 0x2000
	s_addc_u32 s65, s65, 0
	ds_bpermute_b32 v174, v188, v186 offset:28
	s_waitcnt vmcnt(32) lgkmcnt(3)
	v_pk_fma_f32 v[160:161], v[20:21], v[168:169], v[160:161] op_sel_hi:[1,0,1]
	v_pk_fma_f32 v[162:163], v[22:23], v[168:169], v[162:163] op_sel_hi:[1,0,1]
	global_load_dwordx4 v[20:23], v187, s[64:65] nt
	s_add_u32 s64, s64, 0x2000
	s_addc_u32 s65, s65, 0
	ds_bpermute_b32 v168, v188, v186 offset:32
	s_waitcnt vmcnt(32) lgkmcnt(3)
	v_pk_fma_f32 v[164:165], v[24:25], v[170:171], v[164:165] op_sel_hi:[1,0,1]
	v_pk_fma_f32 v[166:167], v[26:27], v[170:171], v[166:167] op_sel_hi:[1,0,1]
	global_load_dwordx4 v[24:27], v187, s[64:65] nt
	s_add_u32 s64, s64, 0x2000
	s_addc_u32 s65, s65, 0
	ds_bpermute_b32 v170, v188, v186 offset:36
	s_waitcnt vmcnt(32) lgkmcnt(3)
	v_pk_fma_f32 v[160:161], v[28:29], v[172:173], v[160:161] op_sel_hi:[1,0,1]
	v_pk_fma_f32 v[162:163], v[30:31], v[172:173], v[162:163] op_sel_hi:[1,0,1]
	global_load_dwordx4 v[28:31], v187, s[64:65] nt
	s_add_u32 s64, s64, 0x2000
	s_addc_u32 s65, s65, 0
	ds_bpermute_b32 v172, v188, v186 offset:40
	s_waitcnt vmcnt(32) lgkmcnt(3)
	v_pk_fma_f32 v[164:165], v[32:33], v[174:175], v[164:165] op_sel_hi:[1,0,1]
	v_pk_fma_f32 v[166:167], v[34:35], v[174:175], v[166:167] op_sel_hi:[1,0,1]
	global_load_dwordx4 v[32:35], v187, s[64:65] nt
	s_add_u32 s64, s64, 0x2000
	s_addc_u32 s65, s65, 0
	ds_bpermute_b32 v174, v188, v186 offset:44
	s_waitcnt vmcnt(32) lgkmcnt(3)
	v_pk_fma_f32 v[160:161], v[36:37], v[168:169], v[160:161] op_sel_hi:[1,0,1]
	v_pk_fma_f32 v[162:163], v[38:39], v[168:169], v[162:163] op_sel_hi:[1,0,1]
	global_load_dwordx4 v[36:39], v187, s[64:65] nt
	s_add_u32 s64, s64, 0x2000
	s_addc_u32 s65, s65, 0
	ds_bpermute_b32 v168, v188, v186 offset:48
	s_waitcnt vmcnt(32) lgkmcnt(3)
	v_pk_fma_f32 v[164:165], v[40:41], v[170:171], v[164:165] op_sel_hi:[1,0,1]
	v_pk_fma_f32 v[166:167], v[42:43], v[170:171], v[166:167] op_sel_hi:[1,0,1]
	global_load_dwordx4 v[40:43], v187, s[64:65] nt
	s_add_u32 s64, s64, 0x2000
	s_addc_u32 s65, s65, 0
	ds_bpermute_b32 v170, v188, v186 offset:52
	s_waitcnt vmcnt(32) lgkmcnt(3)
	v_pk_fma_f32 v[160:161], v[44:45], v[172:173], v[160:161] op_sel_hi:[1,0,1]
	v_pk_fma_f32 v[162:163], v[46:47], v[172:173], v[162:163] op_sel_hi:[1,0,1]
	global_load_dwordx4 v[44:47], v187, s[64:65] nt
	s_add_u32 s64, s64, 0x2000
	s_addc_u32 s65, s65, 0
	ds_bpermute_b32 v172, v188, v186 offset:56
	s_waitcnt vmcnt(32) lgkmcnt(3)
	v_pk_fma_f32 v[164:165], v[48:49], v[174:175], v[164:165] op_sel_hi:[1,0,1]
	v_pk_fma_f32 v[166:167], v[50:51], v[174:175], v[166:167] op_sel_hi:[1,0,1]
	global_load_dwordx4 v[48:51], v187, s[64:65] nt
	s_add_u32 s64, s64, 0x2000
	s_addc_u32 s65, s65, 0
	ds_bpermute_b32 v174, v188, v186 offset:60
	s_waitcnt vmcnt(32) lgkmcnt(3)
	v_pk_fma_f32 v[160:161], v[52:53], v[168:169], v[160:161] op_sel_hi:[1,0,1]
	v_pk_fma_f32 v[162:163], v[54:55], v[168:169], v[162:163] op_sel_hi:[1,0,1]
	global_load_dwordx4 v[52:55], v187, s[64:65] nt
	s_add_u32 s64, s64, 0x2000
	s_addc_u32 s65, s65, 0
	ds_bpermute_b32 v168, v188, v186 offset:64
	s_waitcnt vmcnt(32) lgkmcnt(3)
	v_pk_fma_f32 v[164:165], v[56:57], v[170:171], v[164:165] op_sel_hi:[1,0,1]
	v_pk_fma_f32 v[166:167], v[58:59], v[170:171], v[166:167] op_sel_hi:[1,0,1]
	global_load_dwordx4 v[56:59], v187, s[64:65] nt
	s_add_u32 s64, s64, 0x2000
	s_addc_u32 s65, s65, 0
	ds_bpermute_b32 v170, v188, v186 offset:68
	s_waitcnt vmcnt(32) lgkmcnt(3)
	v_pk_fma_f32 v[160:161], v[60:61], v[172:173], v[160:161] op_sel_hi:[1,0,1]
	v_pk_fma_f32 v[162:163], v[62:63], v[172:173], v[162:163] op_sel_hi:[1,0,1]
	global_load_dwordx4 v[60:63], v187, s[64:65] nt
	s_add_u32 s64, s64, 0x2000
	s_addc_u32 s65, s65, 0
	ds_bpermute_b32 v172, v188, v186 offset:72
	s_waitcnt vmcnt(32) lgkmcnt(3)
	v_pk_fma_f32 v[164:165], v[64:65], v[174:175], v[164:165] op_sel_hi:[1,0,1]
	v_pk_fma_f32 v[166:167], v[66:67], v[174:175], v[166:167] op_sel_hi:[1,0,1]
	global_load_dwordx4 v[64:67], v187, s[64:65] nt
	s_add_u32 s64, s64, 0x2000
	s_addc_u32 s65, s65, 0
	ds_bpermute_b32 v174, v188, v186 offset:76
	s_waitcnt vmcnt(32) lgkmcnt(3)
	v_pk_fma_f32 v[160:161], v[68:69], v[168:169], v[160:161] op_sel_hi:[1,0,1]
	v_pk_fma_f32 v[162:163], v[70:71], v[168:169], v[162:163] op_sel_hi:[1,0,1]
	global_load_dwordx4 v[68:71], v187, s[64:65] nt
	s_add_u32 s64, s64, 0x2000
	s_addc_u32 s65, s65, 0
	ds_bpermute_b32 v168, v188, v186 offset:80
	s_waitcnt vmcnt(32) lgkmcnt(3)
	v_pk_fma_f32 v[164:165], v[72:73], v[170:171], v[164:165] op_sel_hi:[1,0,1]
	v_pk_fma_f32 v[166:167], v[74:75], v[170:171], v[166:167] op_sel_hi:[1,0,1]
	global_load_dwordx4 v[72:75], v187, s[64:65] nt
	s_add_u32 s64, s64, 0x2000
	s_addc_u32 s65, s65, 0
	ds_bpermute_b32 v170, v188, v186 offset:84
	s_waitcnt vmcnt(32) lgkmcnt(3)
; __device__ __forceinline__ void sb_decode_stream(Frame& F, unsigned* qctr, int base, int limit) {
;     ...
;         for (int i = 0; i < 16; ++i) { const float aj = __shfl(a, 32 + 2 * i + half); o4 += aj * B[i]; }
; #pragma unroll
;         for (int i = 0; i < 16; ++i) B[i] = __builtin_nontemporal_load((const f32x4*)(CK + cbn + (size_t)(32 + 2 * i) * stepn));
;         o4.x += __shfl_xor(o4.x, 32); o4.y += __shfl_xor(o4.y, 32); o4.z += __shfl_xor(o4.z, 32); o4.w += __shfl_xor(o4.w, 32);
;         float* P = SSP(S_PART) + ((size_t)bh * DSEG + blk) * DPART;
;         if (half == 0) *(f32x4*)(P + 4 * l32) = o4; if (lane == 0) P[128] = tot;
;         if (!more) break;
;         it = itn; cb = cbn; q4 = q4n;
	v_pk_fma_f32 v[160:161], v[76:77], v[172:173], v[160:161] op_sel_hi:[1,0,1]
	v_pk_fma_f32 v[162:163], v[78:79], v[172:173], v[162:163] op_sel_hi:[1,0,1]
	global_load_dwordx4 v[76:79], v187, s[64:65] nt
	s_add_u32 s64, s64, 0x2000
	s_addc_u32 s65, s65, 0
	ds_bpermute_b32 v172, v188, v186 offset:88
	s_waitcnt vmcnt(32) lgkmcnt(3)
	v_pk_fma_f32 v[164:165], v[80:81], v[174:175], v[164:165] op_sel_hi:[1,0,1]
	v_pk_fma_f32 v[166:167], v[82:83], v[174:175], v[166:167] op_sel_hi:[1,0,1]
	global_load_dwordx4 v[80:83], v187, s[64:65] nt
	s_add_u32 s64, s64, 0x2000
	s_addc_u32 s65, s65, 0
	ds_bpermute_b32 v174, v188, v186 offset:92
	s_waitcnt vmcnt(32) lgkmcnt(3)
	v_pk_fma_f32 v[160:161], v[84:85], v[168:169], v[160:161] op_sel_hi:[1,0,1]
	v_pk_fma_f32 v[162:163], v[86:87], v[168:169], v[162:163] op_sel_hi:[1,0,1]
	global_load_dwordx4 v[84:87], v187, s[64:65] nt
	s_add_u32 s64, s64, 0x2000
	s_addc_u32 s65, s65, 0
	ds_bpermute_b32 v168, v188, v186 offset:96
	s_waitcnt vmcnt(32) lgkmcnt(3)
	v_pk_fma_f32 v[164:165], v[88:89], v[170:171], v[164:165] op_sel_hi:[1,0,1]
	v_pk_fma_f32 v[166:167], v[90:91], v[170:171], v[166:167] op_sel_hi:[1,0,1]
	global_load_dwordx4 v[88:91], v187, s[64:65] nt
	s_add_u32 s64, s64, 0x2000
	s_addc_u32 s65, s65, 0
	ds_bpermute_b32 v170, v188, v186 offset:100
	s_waitcnt vmcnt(32) lgkmcnt(3)
	v_pk_fma_f32 v[160:161], v[92:93], v[172:173], v[160:161] op_sel_hi:[1,0,1]
	v_pk_fma_f32 v[162:163], v[94:95], v[172:173], v[162:163] op_sel_hi:[1,0,1]
	global_load_dwordx4 v[92:95], v187, s[64:65] nt
	s_add_u32 s64, s64, 0x2000
	s_addc_u32 s65, s65, 0
	ds_bpermute_b32 v172, v188, v186 offset:104
	s_waitcnt vmcnt(32) lgkmcnt(3)
	v_pk_fma_f32 v[164:165], v[96:97], v[174:175], v[164:165] op_sel_hi:[1,0,1]
	v_pk_fma_f32 v[166:167], v[98:99], v[174:175], v[166:167] op_sel_hi:[1,0,1]
	global_load_dwordx4 v[96:99], v187, s[64:65] nt
	s_add_u32 s64, s64, 0x2000
	s_addc_u32 s65, s65, 0
	ds_bpermute_b32 v174, v188, v186 offset:108
	s_waitcnt vmcnt(32) lgkmcnt(3)
	v_pk_fma_f32 v[160:161], v[100:101], v[168:169], v[160:161] op_sel_hi:[1,0,1]
	v_pk_fma_f32 v[162:163], v[102:103], v[168:169], v[162:163] op_sel_hi:[1,0,1]
	global_load_dwordx4 v[100:103], v187, s[64:65] nt
	s_add_u32 s64, s64, 0x2000
	s_addc_u32 s65, s65, 0
	ds_bpermute_b32 v168, v188, v186 offset:112
	s_waitcnt vmcnt(32) lgkmcnt(3)
	v_pk_fma_f32 v[164:165], v[104:105], v[170:171], v[164:165] op_sel_hi:[1,0,1]
	v_pk_fma_f32 v[166:167], v[106:107], v[170:171], v[166:167] op_sel_hi:[1,0,1]
	global_load_dwordx4 v[104:107], v187, s[64:65] nt
	s_add_u32 s64, s64, 0x2000
	s_addc_u32 s65, s65, 0
	ds_bpermute_b32 v170, v188, v186 offset:116
	s_waitcnt vmcnt(32) lgkmcnt(3)
	v_pk_fma_f32 v[160:161], v[108:109], v[172:173], v[160:161] op_sel_hi:[1,0,1]
	v_pk_fma_f32 v[162:163], v[110:111], v[172:173], v[162:163] op_sel_hi:[1,0,1]
	global_load_dwordx4 v[108:111], v187, s[64:65] nt
	s_add_u32 s64, s64, 0x2000
	s_addc_u32 s65, s65, 0
	ds_bpermute_b32 v172, v188, v186 offset:120
	s_waitcnt vmcnt(32) lgkmcnt(3)
	v_pk_fma_f32 v[164:165], v[112:113], v[174:175], v[164:165] op_sel_hi:[1,0,1]
	v_pk_fma_f32 v[166:167], v[114:115], v[174:175], v[166:167] op_sel_hi:[1,0,1]
	global_load_dwordx4 v[112:115], v187, s[64:65] nt
	s_add_u32 s64, s64, 0x2000
	s_addc_u32 s65, s65, 0
	ds_bpermute_b32 v174, v188, v186 offset:124
	s_waitcnt vmcnt(32) lgkmcnt(3)
	v_pk_fma_f32 v[160:161], v[116:117], v[168:169], v[160:161] op_sel_hi:[1,0,1]
	v_pk_fma_f32 v[162:163], v[118:119], v[168:169], v[162:163] op_sel_hi:[1,0,1]
	global_load_dwordx4 v[116:119], v187, s[64:65] nt
	s_add_u32 s64, s64, 0x2000
	s_addc_u32 s65, s65, 0
	s_waitcnt vmcnt(32) lgkmcnt(2)
	v_pk_fma_f32 v[164:165], v[120:121], v[170:171], v[164:165] op_sel_hi:[1,0,1]
	v_pk_fma_f32 v[166:167], v[122:123], v[170:171], v[166:167] op_sel_hi:[1,0,1]
	global_load_dwordx4 v[120:123], v187, s[64:65] nt
	s_add_u32 s64, s64, 0x2000
	s_addc_u32 s65, s65, 0
	s_waitcnt vmcnt(32) lgkmcnt(1)
	v_pk_fma_f32 v[160:161], v[124:125], v[172:173], v[160:161] op_sel_hi:[1,0,1]
	v_pk_fma_f32 v[162:163], v[126:127], v[172:173], v[162:163] op_sel_hi:[1,0,1]
	global_load_dwordx4 v[124:127], v187, s[64:65] nt
	s_add_u32 s64, s64, 0x2000
	s_addc_u32 s65, s65, 0
	s_waitcnt vmcnt(32) lgkmcnt(0)
	v_pk_fma_f32 v[164:165], v[128:129], v[174:175], v[164:165] op_sel_hi:[1,0,1]
	v_pk_fma_f32 v[166:167], v[130:131], v[174:175], v[166:167] op_sel_hi:[1,0,1]
	global_load_dwordx4 v[128:131], v187, s[64:65] nt
	s_add_u32 s64, s64, 0x2000
	s_addc_u32 s65, s65, 0
	v_pk_add_f32 v[160:161], v[160:161], v[164:165]
	v_pk_add_f32 v[162:163], v[162:163], v[166:167]
	v_mov_b32_e32 v164, v160
	v_mov_b32_e32 v165, v161
	v_mov_b32_e32 v166, v162
	v_mov_b32_e32 v167, v163
	v_permlane32_swap_b32_e32 v160, v164
	v_permlane32_swap_b32_e32 v161, v165
	v_permlane32_swap_b32_e32 v162, v166
	v_permlane32_swap_b32_e32 v163, v167
	v_pk_add_f32 v[160:161], v[160:161], v[164:165]
	v_pk_add_f32 v[162:163], v[162:163], v[166:167]
	s_mov_b32 exec_hi, 0
	global_store_dwordx4 v193, v[160:163], s[70:71]
	s_mov_b32 exec_lo, 1
	global_store_dword v189, v183, s[70:71] offset:512
	s_mov_b64 exec, -1
	s_mov_b32 s72, s73
	s_branch .Ldqc_loop

; __device__ __forceinline__ int dq_first(Frame& F, unsigned* q) {
;     if (F.tid == 64) F.MISC[20] = __hip_atomic_fetch_add(q, 1u, __ATOMIC_RELAXED, __HIP_MEMORY_SCOPE_AGENT);
;     __syncthreads();
; __device__ __forceinline__ void p2_mixers(Frame& F, unsigned* qctr) {
;     ...
;     { unsigned* aq = qctr + 192; int cur = dq_first(F, aq), par = 0;
;       while (cur < 512) {
;           unsigned nxt = 0; if (F.tid == 64) nxt = __hip_atomic_fetch_add(aq, 1u, __ATOMIC_RELAXED, __HIP_MEMORY_SCOPE_AGENT);
.Ldqc_exit:
.LBB0_1420:
	s_waitcnt lgkmcnt(0)
	s_add_u32 s42, s26, 0x1300
	s_addc_u32 s43, s27, 0
	v_cmp_eq_u32_e64 s[6:7], 64, v0
	s_and_saveexec_b64 s[8:9], s[6:7]
	s_cbranch_execz .LBB0_1424
	s_mov_b64 s[12:13], exec
	v_mbcnt_lo_u32_b32 v1, s12, 0
	v_mbcnt_hi_u32_b32 v1, s13, v1
	v_cmp_eq_u32_e32 vcc, 0, v1
	s_and_saveexec_b64 s[10:11], vcc
	s_cbranch_execz .LBB0_1423
	s_bcnt1_i32_b64 s2, s[12:13]
	s_waitcnt vmcnt(32)
	v_mov_b32_e32 v2, 0
	v_mov_b32_e32 v3, s2
	global_atomic_add v2, v2, v3, s[42:43] sc0

; __device__ __forceinline__ void sb_decode_stream(Frame& F, unsigned* qctr, int base, int limit) {
;     const float* CK = kin(2); const float* CV = kin(3); const int* PT = (const int*)kin(4);
;     int lane = F.lane; asm volatile("" : "+v"(lane));
;     const int half = lane >> 5, l32 = lane & 31;
;     const float k1 = SB_SCALE * 1.4426950408889634f;
;     const size_t lo = (size_t)half * (NH * HD) + 4 * l32;
;     int it;
;     { const unsigned v = __hip_atomic_fetch_add(qctr, 1u, __ATOMIC_RELAXED, __HIP_MEMORY_SCOPE_AGENT);
;       it = (int)(__builtin_amdgcn_readfirstlane(v) >> 6); if (it >= limit) return; it += base; }
; __device__ __forceinline__ void p2_mixers(Frame& F, unsigned* qctr) {
;     ...
;     sb_decode_stream(F, qctr + 64, DEC_Q2, DEC_ITEMS - DEC_Q2);
.LBB0_1449:
	s_load_dwordx2 s[50:51], s[0:1], 0x10
	s_load_dwordx2 s[52:53], s[0:1], 0x18
	s_load_dwordx2 s[54:55], s[0:1], 0x20
	s_load_dwordx2 s[56:57], s[0:1], 0x60
	s_add_u32 s58, s26, 0x1100
	s_addc_u32 s59, s27, 0
	s_add_u32 s60, s26, 0x2ff18000
	s_addc_u32 s61, s27, 0
	s_add_u32 s62, s26, 0x2ff70400
	s_addc_u32 s63, s27, 0
	s_mov_b32 s76, 0xcccccccc
	s_mov_b32 s77, 0xcccccccc
	s_mov_b32 s78, 0xaaaaaaaa
	s_mov_b32 s79, 0xaaaaaaaa
	v_and_b32_e32 v193, 31, v199
	v_lshrrev_b32_e32 v188, 5, v199
	v_lshlrev_b32_e32 v193, 4, v193
	v_lshl_add_u32 v187, v188, 12, v193
	v_lshlrev_b32_e32 v188, 7, v188
	v_mov_b32_e32 v189, 0
	v_mov_b32_e32 v190, 64
	v_mov_b32_e32 v190, 0x200
	s_mov_b32 s37, 0x251e0
	s_cmp_eq_u32 s94, 0
	s_cbranch_scc0 .Ldqd_pro
	s_mov_b64 exec, 1
	global_atomic_add v191, v189, v190, s[58:59] sc0
	s_mov_b64 exec, -1

; __device__ __forceinline__ unsigned xb_ld(unsigned* p)              { return __hip_atomic_load(p, __ATOMIC_RELAXED, __HIP_MEMORY_SCOPE_AGENT); }
; __device__ __forceinline__ void xcd_barrier_complete(unsigned* bar, unsigned x, unsigned& nloc, unsigned& nx) {
;     const unsigned G = gridDim.x * gridDim.y * gridDim.z;
;     unsigned sum, cnt, mine, sp = 0u;
;     for (;;) {
;         sum = 0u; cnt = 0u; mine = 0u;
; #pragma unroll
;         for (unsigned j = 0; j < 16; ++j) { const unsigned c = xb_ld(&bar[XB_XCNT(j)]); sum += c; cnt += (c > 0u) ? 1u : 0u; mine = (j == x) ? c : mine; }
; __device__ __forceinline__ void xcd_barrier(const XcdBarrier& b) {
;     asm volatile("s_waitcnt vmcnt(0)" ::: "memory");
;     __syncthreads();
;     if (threadIdx.x == 0) {
;         unsigned* bar = b.bar;
;         __builtin_amdgcn_s_waitcnt(0);
;         unsigned nloc = b.st[0], nx = b.st[1];
;         if (nloc == 0u) { xcd_barrier_complete(bar, b.x, nloc, nx); b.st[0] = nloc; b.st[1] = nx; }
.Ldqd_exit:
.LBB0_1460:
	s_waitcnt vmcnt(0)
	s_waitcnt lgkmcnt(0)
	s_barrier
	s_mov_b64 s[2:3], exec
	v_readlane_b32 s4, v251, 3
	v_readlane_b32 s5, v251, 4
	s_and_b64 s[4:5], s[2:3], s[4:5]
	s_xor_b64 s[6:7], s[4:5], s[2:3]
	s_mov_b64 exec, s[4:5]
	s_cbranch_execz .LBB0_1513
	s_add_i32 s2, 0, 0x25160
	v_mov_b32_e32 v1, s2
	s_waitcnt vmcnt(0) expcnt(0) lgkmcnt(0)
	ds_read_b32 v3, v1
	s_add_i32 s2, 0, 0x25164
	v_mov_b32_e32 v1, s2
	ds_read_b32 v1, v1
	s_waitcnt lgkmcnt(1)
	v_cmp_ne_u32_e32 vcc, 0, v3
	s_cbranch_vccnz .LBB0_1476
	s_add_u32 s8, s26, 0x4200
	s_addc_u32 s9, s27, 0
	s_add_u32 s10, s26, 0x4400
	s_addc_u32 s11, s27, 0
	s_add_u32 s12, s26, 0x4500
	s_addc_u32 s13, s27, 0
	s_add_u32 s14, s26, 0x4600
	s_addc_u32 s15, s27, 0
	s_add_u32 s16, s26, 0x4700
	s_addc_u32 s17, s27, 0
	s_add_u32 s18, s26, 0x4800
	s_addc_u32 s19, s27, 0
	s_add_u32 s20, s26, 0x4900
	s_addc_u32 s21, s27, 0
	s_add_u32 s38, s26, 0x4a00
	s_addc_u32 s39, s27, 0
	s_add_u32 s40, s26, 0x4b00
	s_addc_u32 s41, s27, 0
	s_add_u32 s42, s26, 0x4c00
	s_addc_u32 s43, s27, 0
	s_add_u32 s44, s26, 0x4d00
	s_addc_u32 s45, s27, 0
	s_add_u32 s46, s26, 0x4e00
	s_addc_u32 s47, s27, 0
	s_add_u32 s48, s26, 0x4f00
	v_readlane_b32 s4, v251, 0
	s_addc_u32 s49, s27, 0
	v_readlane_b32 s5, v251, 1
	s_add_u32 s50, s26, 0x5000
	s_load_dwordx2 s[2:3], s[4:5], 0x4
	s_addc_u32 s51, s27, 0
	s_add_u32 s52, s26, 0x5100
	s_addc_u32 s53, s27, 0
	s_add_u32 s54, s26, 0x5200
	s_addc_u32 s55, s27, 0
	s_waitcnt lgkmcnt(0)
	s_mul_i32 s2, s2, s34
	s_add_u32 s56, s26, 0x5300
	s_mul_i32 s2, s2, s3
	s_addc_u32 s57, s27, 0
	s_mov_b32 s3, 1
	v_mov_b32_e32 v17, 0
	s_branch .LBB0_1464
